# deferred routine publishes with write-through (sc1) stores and no buffer_wbl2 (the L2 write-back at publish was flushing the XCD's dirty in-proj outputs on the tail)
# speedup vs baseline: 1.0041x; 1.0028x over previous
; #define LAS __attribute__((address_space(3)))
; __device__ __forceinline__ unsigned pk2(float lo, float hi) { return pg8::cvt_pk_bf16(lo, hi); }
; __device__ __forceinline__ void tr_item(const float* W, int ldw, int K, int k0, int sc0, bf16* WT, int dr0, const float* gain, float cs, LAS float* scr, int lane) {
; #pragma unroll 16
;     for (int i = 0; i < 32; ++i) { const int kk = 2 * i + (lane >> 5); const float g = gain ? gain[k0 + kk] * cs : cs;
;         scr[kk * 33 + (lane & 31)] = W[(size_t)(k0 + kk) * ldw + sc0 + (lane & 31)] * g; }
;     asm volatile("s_waitcnt lgkmcnt(0)" ::: "memory");
;     const int c = lane & 7;
; #pragma unroll
;     for (int j = 0; j < 4; ++j) { const int n = (lane >> 3) + 8 * j; const LAS float* s = scr + (8 * c) * 33 + n;
;         u32x4 o; o.x = pk2(s[0 * 33], s[1 * 33]); o.y = pk2(s[2 * 33], s[3 * 33]); o.z = pk2(s[4 * 33], s[5 * 33]); o.w = pk2(s[6 * 33], s[7 * 33]);
;         *(u32x4*)(WT + (size_t)(dr0 + n) * K + k0 + 8 * c) = o; }
;     asm volatile("s_waitcnt lgkmcnt(0)" ::: "memory");
; }
; __global__ void __launch_bounds__(NTHR, 2) hybrid_fwd(Args args) {
;     ...
;         for (int bi = blk; bi < 128; bi += G) { const int nb = bi >> 3, kl = bi & 7, k0 = kl * 64 + wave * 8, gb = (k0 >> 7) * 128, n = nb * 64 + lane;
;             float a[8];
; #pragma unroll
;             for (int kk = 0; kk < 8; ++kk) a[kk] = 0.f;
; #pragma unroll 8
.Ldef_scale:
	v_mul_f32_e32 v0, v0, v32
	v_mul_f32_e32 v1, v1, v33
	v_mul_f32_e32 v2, v2, v34
	v_mul_f32_e32 v3, v3, v35
	v_mul_f32_e32 v4, v4, v36
	v_mul_f32_e32 v5, v5, v37
	v_mul_f32_e32 v6, v6, v38
	v_mul_f32_e32 v7, v7, v39
	v_mul_f32_e32 v8, v8, v40
	v_mul_f32_e32 v9, v9, v41
	v_mul_f32_e32 v10, v10, v42
	v_mul_f32_e32 v11, v11, v43
	v_mul_f32_e32 v12, v12, v44
	v_mul_f32_e32 v13, v13, v45
	v_mul_f32_e32 v14, v14, v46
	v_mul_f32_e32 v15, v15, v47
	v_mul_f32_e32 v16, v16, v48
	v_mul_f32_e32 v17, v17, v49
	v_mul_f32_e32 v18, v18, v50
	v_mul_f32_e32 v19, v19, v51
	v_mul_f32_e32 v20, v20, v52
	v_mul_f32_e32 v21, v21, v53
	v_mul_f32_e32 v22, v22, v54
	v_mul_f32_e32 v23, v23, v55
	v_mul_f32_e32 v24, v24, v56
	v_mul_f32_e32 v25, v25, v57
	v_mul_f32_e32 v26, v26, v58
	v_mul_f32_e32 v27, v27, v59
	v_mul_f32_e32 v28, v28, v60
	v_mul_f32_e32 v29, v29, v61
	v_mul_f32_e32 v30, v30, v62
	v_mul_f32_e32 v31, v31, v63
	ds_write_b32 v86, v0 offset:0
	ds_write_b32 v86, v1 offset:264
	ds_write_b32 v86, v2 offset:528
	ds_write_b32 v86, v3 offset:792
	ds_write_b32 v86, v4 offset:1056
	ds_write_b32 v86, v5 offset:1320
	ds_write_b32 v86, v6 offset:1584
	ds_write_b32 v86, v7 offset:1848
	ds_write_b32 v86, v8 offset:2112
	ds_write_b32 v86, v9 offset:2376
	ds_write_b32 v86, v10 offset:2640
	ds_write_b32 v86, v11 offset:2904
	ds_write_b32 v86, v12 offset:3168
	ds_write_b32 v86, v13 offset:3432
	ds_write_b32 v86, v14 offset:3696
	ds_write_b32 v86, v15 offset:3960
	ds_write_b32 v86, v16 offset:4224
	ds_write_b32 v86, v17 offset:4488
	ds_write_b32 v86, v18 offset:4752
	ds_write_b32 v86, v19 offset:5016
	ds_write_b32 v86, v20 offset:5280
	ds_write_b32 v86, v21 offset:5544
	ds_write_b32 v86, v22 offset:5808
	ds_write_b32 v86, v23 offset:6072
	ds_write_b32 v86, v24 offset:6336
	ds_write_b32 v86, v25 offset:6600
	ds_write_b32 v86, v26 offset:6864
	ds_write_b32 v86, v27 offset:7128
	ds_write_b32 v86, v28 offset:7392
	ds_write_b32 v86, v29 offset:7656
	ds_write_b32 v86, v30 offset:7920
	ds_write_b32 v86, v31 offset:8184
	s_waitcnt lgkmcnt(0)
	s_mul_i32 s79, s28, s30
	s_lshl_b32 s88, s27, 1
	s_add_u32 s79, s79, s88
	s_add_u32 s86, s12, s79
	s_addc_u32 s87, s13, 0
	s_lshl_b32 s89, s30, 3
	v_mad_u32_u24 v88, v83, s30, v82
	ds_read2_b32 v[64:65], v87 offset0:0 offset1:33
	ds_read2_b32 v[66:67], v87 offset0:66 offset1:99
	ds_read2_b32 v[68:69], v87 offset0:132 offset1:165
	ds_read2_b32 v[70:71], v87 offset0:198 offset1:231
	s_waitcnt lgkmcnt(0)
	v_cvt_pk_bf16_f32 v72, v64, v65
	v_cvt_pk_bf16_f32 v73, v66, v67
	v_cvt_pk_bf16_f32 v74, v68, v69
	v_cvt_pk_bf16_f32 v75, v70, v71
	global_store_dwordx4 v88, v[72:75], s[86:87] sc1
	s_add_u32 s86, s86, s89
	s_addc_u32 s87, s87, 0
	s_nop 1
	ds_read2_b32 v[64:65], v87 offset0:8 offset1:41
	ds_read2_b32 v[66:67], v87 offset0:74 offset1:107
	ds_read2_b32 v[68:69], v87 offset0:140 offset1:173
	ds_read2_b32 v[70:71], v87 offset0:206 offset1:239
	s_waitcnt lgkmcnt(0)
	v_cvt_pk_bf16_f32 v72, v64, v65
	v_cvt_pk_bf16_f32 v73, v66, v67
	v_cvt_pk_bf16_f32 v74, v68, v69
	v_cvt_pk_bf16_f32 v75, v70, v71
	global_store_dwordx4 v88, v[72:75], s[86:87] sc1
	s_add_u32 s86, s86, s89
	s_addc_u32 s87, s87, 0
	s_nop 1
	ds_read2_b32 v[64:65], v87 offset0:16 offset1:49
	ds_read2_b32 v[66:67], v87 offset0:82 offset1:115
	ds_read2_b32 v[68:69], v87 offset0:148 offset1:181
	ds_read2_b32 v[70:71], v87 offset0:214 offset1:247
	s_waitcnt lgkmcnt(0)
	v_cvt_pk_bf16_f32 v72, v64, v65
	v_cvt_pk_bf16_f32 v73, v66, v67
	v_cvt_pk_bf16_f32 v74, v68, v69
	v_cvt_pk_bf16_f32 v75, v70, v71
	global_store_dwordx4 v88, v[72:75], s[86:87] sc1
	s_add_u32 s86, s86, s89
	s_addc_u32 s87, s87, 0
	s_nop 1
	ds_read2_b32 v[64:65], v87 offset0:24 offset1:57
	ds_read2_b32 v[66:67], v87 offset0:90 offset1:123
	ds_read2_b32 v[68:69], v87 offset0:156 offset1:189
	ds_read2_b32 v[70:71], v87 offset0:222 offset1:255
	s_waitcnt lgkmcnt(0)
	v_cvt_pk_bf16_f32 v72, v64, v65
	v_cvt_pk_bf16_f32 v73, v66, v67
	v_cvt_pk_bf16_f32 v74, v68, v69
	v_cvt_pk_bf16_f32 v75, v70, v71
	global_store_dwordx4 v88, v[72:75], s[86:87] sc1
	s_waitcnt lgkmcnt(0)
	s_addk_i32 s77, 0x600
	s_branch .Ldef_item
.Ldef_items_done:
	s_cmp_ge_u32 s2, 192
	s_cbranch_scc1 .Ldef_fold_done
	s_load_dwordx2 s[8:9], s[0:1], 0x30
	s_load_dwordx2 s[10:11], s[0:1], 0x38
	s_load_dwordx2 s[12:13], s[0:1], 0x40
	s_sub_i32 s24, s2, 64
	s_lshr_b32 s25, s24, 3
	s_and_b32 s26, s24, 7
	s_lshl_b32 s27, s26, 6
	s_lshl_b32 s79, s74, 3
	s_add_i32 s27, s27, s79
	s_and_b32 s28, s27, 0xffffff80
	s_lshl_b32 s29, s25, 6
	v_add_u32_e32 v155, s29, v212
	v_lshlrev_b32_e32 v156, 2, v155
	v_lshlrev_b32_e32 v157, 2, v212
	s_waitcnt lgkmcnt(0)
; __global__ void __launch_bounds__(NTHR, 2) hybrid_fwd(Args args) {
;     ...
;         for (int bi = blk; bi < 128; bi += G) { const int nb = bi >> 3, kl = bi & 7, k0 = kl * 64 + wave * 8, gb = (k0 >> 7) * 128, n = nb * 64 + lane;
;             float a[8];
; #pragma unroll
;             for (int kk = 0; kk < 8; ++kk) a[kk] = 0.f;
; #pragma unroll 8
;             for (int d = 0; d < 128; ++d) { const float wv = w_pool_out[(size_t)(gb + d) * 1024 + n] * pool_scale[gb + d];
; #pragma unroll
;                 for (int kk = 0; kk < 8; ++kk) a[kk] += pool_w[(size_t)(k0 + kk) * 128 + d] * wv; }
	s_lshl_b32 s79, s28, 12
	s_add_u32 s82, s12, s79
	s_addc_u32 s83, s13, 0
	global_load_dword v0, v156, s[82:83] nt
	s_add_u32 s82, s82, 0x1000
	s_addc_u32 s83, s83, 0
	global_load_dword v1, v156, s[82:83] nt
	s_add_u32 s82, s82, 0x1000
	s_addc_u32 s83, s83, 0
	global_load_dword v2, v156, s[82:83] nt
	s_add_u32 s82, s82, 0x1000
	s_addc_u32 s83, s83, 0
	global_load_dword v3, v156, s[82:83] nt
	s_add_u32 s82, s82, 0x1000
	s_addc_u32 s83, s83, 0
	global_load_dword v4, v156, s[82:83] nt
	s_add_u32 s82, s82, 0x1000
	s_addc_u32 s83, s83, 0
	global_load_dword v5, v156, s[82:83] nt
	s_add_u32 s82, s82, 0x1000
	s_addc_u32 s83, s83, 0
	global_load_dword v6, v156, s[82:83] nt
	s_add_u32 s82, s82, 0x1000
	s_addc_u32 s83, s83, 0
	global_load_dword v7, v156, s[82:83] nt
	s_add_u32 s82, s82, 0x1000
	s_addc_u32 s83, s83, 0
	global_load_dword v8, v156, s[82:83] nt
	s_add_u32 s82, s82, 0x1000
	s_addc_u32 s83, s83, 0
	global_load_dword v9, v156, s[82:83] nt
	s_add_u32 s82, s82, 0x1000
	s_addc_u32 s83, s83, 0
	global_load_dword v10, v156, s[82:83] nt
	s_add_u32 s82, s82, 0x1000
	s_addc_u32 s83, s83, 0
	global_load_dword v11, v156, s[82:83] nt
	s_add_u32 s82, s82, 0x1000
	s_addc_u32 s83, s83, 0
	global_load_dword v12, v156, s[82:83] nt
	s_add_u32 s82, s82, 0x1000
	s_addc_u32 s83, s83, 0
	global_load_dword v13, v156, s[82:83] nt
	s_add_u32 s82, s82, 0x1000
	s_addc_u32 s83, s83, 0
	global_load_dword v14, v156, s[82:83] nt
	s_add_u32 s82, s82, 0x1000
	s_addc_u32 s83, s83, 0
	global_load_dword v15, v156, s[82:83] nt
	s_add_u32 s82, s82, 0x1000
	s_addc_u32 s83, s83, 0
	global_load_dword v16, v156, s[82:83] nt
	s_add_u32 s82, s82, 0x1000
	s_addc_u32 s83, s83, 0
	global_load_dword v17, v156, s[82:83] nt
	s_add_u32 s82, s82, 0x1000
	s_addc_u32 s83, s83, 0
	global_load_dword v18, v156, s[82:83] nt
	s_add_u32 s82, s82, 0x1000
	s_addc_u32 s83, s83, 0
	global_load_dword v19, v156, s[82:83] nt
	s_add_u32 s82, s82, 0x1000
	s_addc_u32 s83, s83, 0
	global_load_dword v20, v156, s[82:83] nt
	s_add_u32 s82, s82, 0x1000
	s_addc_u32 s83, s83, 0
	global_load_dword v21, v156, s[82:83] nt
	s_add_u32 s82, s82, 0x1000
	s_addc_u32 s83, s83, 0
	global_load_dword v22, v156, s[82:83] nt
	s_add_u32 s82, s82, 0x1000
	s_addc_u32 s83, s83, 0
	global_load_dword v23, v156, s[82:83] nt
	s_add_u32 s82, s82, 0x1000
	s_addc_u32 s83, s83, 0
	global_load_dword v24, v156, s[82:83] nt
	s_add_u32 s82, s82, 0x1000
	s_addc_u32 s83, s83, 0
	global_load_dword v25, v156, s[82:83] nt
	s_add_u32 s82, s82, 0x1000
	s_addc_u32 s83, s83, 0
	global_load_dword v26, v156, s[82:83] nt
	s_add_u32 s82, s82, 0x1000
	s_addc_u32 s83, s83, 0
	global_load_dword v27, v156, s[82:83] nt
	s_add_u32 s82, s82, 0x1000
	s_addc_u32 s83, s83, 0
	global_load_dword v28, v156, s[82:83] nt
	s_add_u32 s82, s82, 0x1000
	s_addc_u32 s83, s83, 0
	global_load_dword v29, v156, s[82:83] nt
	s_add_u32 s82, s82, 0x1000
	s_addc_u32 s83, s83, 0
	global_load_dword v30, v156, s[82:83] nt
	s_add_u32 s82, s82, 0x1000
	s_addc_u32 s83, s83, 0
	global_load_dword v31, v156, s[82:83] nt
	s_add_u32 s82, s82, 0x1000
	s_addc_u32 s83, s83, 0
	global_load_dword v32, v156, s[82:83] nt
	s_add_u32 s82, s82, 0x1000
	s_addc_u32 s83, s83, 0
	global_load_dword v33, v156, s[82:83] nt
	s_add_u32 s82, s82, 0x1000
	s_addc_u32 s83, s83, 0
	global_load_dword v34, v156, s[82:83] nt
	s_add_u32 s82, s82, 0x1000
	s_addc_u32 s83, s83, 0
	global_load_dword v35, v156, s[82:83] nt
	s_add_u32 s82, s82, 0x1000
	s_addc_u32 s83, s83, 0
	global_load_dword v36, v156, s[82:83] nt
	s_add_u32 s82, s82, 0x1000
	s_addc_u32 s83, s83, 0
	global_load_dword v37, v156, s[82:83] nt
	s_add_u32 s82, s82, 0x1000
	s_addc_u32 s83, s83, 0
	global_load_dword v38, v156, s[82:83] nt
	s_add_u32 s82, s82, 0x1000
	s_addc_u32 s83, s83, 0
	global_load_dword v39, v156, s[82:83] nt
	s_add_u32 s82, s82, 0x1000
	s_addc_u32 s83, s83, 0
	global_load_dword v40, v156, s[82:83] nt
	s_add_u32 s82, s82, 0x1000
	s_addc_u32 s83, s83, 0
	global_load_dword v41, v156, s[82:83] nt
	s_add_u32 s82, s82, 0x1000
	s_addc_u32 s83, s83, 0
	global_load_dword v42, v156, s[82:83] nt
	s_add_u32 s82, s82, 0x1000
	s_addc_u32 s83, s83, 0
	global_load_dword v43, v156, s[82:83] nt
	s_add_u32 s82, s82, 0x1000
	s_addc_u32 s83, s83, 0
	global_load_dword v44, v156, s[82:83] nt
	s_add_u32 s82, s82, 0x1000
	s_addc_u32 s83, s83, 0
	global_load_dword v45, v156, s[82:83] nt
	s_add_u32 s82, s82, 0x1000
	s_addc_u32 s83, s83, 0
	global_load_dword v46, v156, s[82:83] nt
	s_add_u32 s82, s82, 0x1000
	s_addc_u32 s83, s83, 0
	global_load_dword v47, v156, s[82:83] nt
	s_add_u32 s82, s82, 0x1000
	s_addc_u32 s83, s83, 0
	global_load_dword v48, v156, s[82:83] nt
	s_add_u32 s82, s82, 0x1000
	s_addc_u32 s83, s83, 0
	global_load_dword v49, v156, s[82:83] nt
	s_add_u32 s82, s82, 0x1000
	s_addc_u32 s83, s83, 0
	global_load_dword v50, v156, s[82:83] nt
	s_add_u32 s82, s82, 0x1000
	s_addc_u32 s83, s83, 0
	global_load_dword v51, v156, s[82:83] nt
	s_add_u32 s82, s82, 0x1000
	s_addc_u32 s83, s83, 0
	global_load_dword v52, v156, s[82:83] nt
	s_add_u32 s82, s82, 0x1000
	s_addc_u32 s83, s83, 0
	global_load_dword v53, v156, s[82:83] nt
	s_add_u32 s82, s82, 0x1000
	s_addc_u32 s83, s83, 0
	global_load_dword v54, v156, s[82:83] nt
	s_add_u32 s82, s82, 0x1000
	s_addc_u32 s83, s83, 0
	global_load_dword v55, v156, s[82:83] nt
	s_add_u32 s82, s82, 0x1000
	s_addc_u32 s83, s83, 0
	global_load_dword v56, v156, s[82:83] nt
	s_add_u32 s82, s82, 0x1000
	s_addc_u32 s83, s83, 0
	global_load_dword v57, v156, s[82:83] nt
	s_add_u32 s82, s82, 0x1000
	s_addc_u32 s83, s83, 0
	global_load_dword v58, v156, s[82:83] nt
	s_add_u32 s82, s82, 0x1000
	s_addc_u32 s83, s83, 0
	global_load_dword v59, v156, s[82:83] nt
; __global__ void __launch_bounds__(NTHR, 2) hybrid_fwd(Args args) {
;     ...
; #pragma unroll 8
;             for (int d = 0; d < 128; ++d) { const float wv = w_pool_out[(size_t)(gb + d) * 1024 + n] * pool_scale[gb + d];
	s_add_u32 s82, s82, 0x1000
	s_addc_u32 s83, s83, 0
	global_load_dword v60, v156, s[82:83] nt
	s_add_u32 s82, s82, 0x1000
	s_addc_u32 s83, s83, 0
	global_load_dword v61, v156, s[82:83] nt
	s_add_u32 s82, s82, 0x1000
	s_addc_u32 s83, s83, 0
	global_load_dword v62, v156, s[82:83] nt
	s_add_u32 s82, s82, 0x1000
	s_addc_u32 s83, s83, 0
	global_load_dword v63, v156, s[82:83] nt
	s_add_u32 s82, s82, 0x1000
	s_addc_u32 s83, s83, 0
	global_load_dword v64, v156, s[82:83] nt
	s_add_u32 s82, s82, 0x1000
	s_addc_u32 s83, s83, 0
	global_load_dword v65, v156, s[82:83] nt
	s_add_u32 s82, s82, 0x1000
	s_addc_u32 s83, s83, 0
	global_load_dword v66, v156, s[82:83] nt
	s_add_u32 s82, s82, 0x1000
	s_addc_u32 s83, s83, 0
	global_load_dword v67, v156, s[82:83] nt
	s_add_u32 s82, s82, 0x1000
	s_addc_u32 s83, s83, 0
	global_load_dword v68, v156, s[82:83] nt
	s_add_u32 s82, s82, 0x1000
	s_addc_u32 s83, s83, 0
	global_load_dword v69, v156, s[82:83] nt
	s_add_u32 s82, s82, 0x1000
	s_addc_u32 s83, s83, 0
	global_load_dword v70, v156, s[82:83] nt
	s_add_u32 s82, s82, 0x1000
	s_addc_u32 s83, s83, 0
	global_load_dword v71, v156, s[82:83] nt
	s_add_u32 s82, s82, 0x1000
	s_addc_u32 s83, s83, 0
	global_load_dword v72, v156, s[82:83] nt
	s_add_u32 s82, s82, 0x1000
	s_addc_u32 s83, s83, 0
	global_load_dword v73, v156, s[82:83] nt
	s_add_u32 s82, s82, 0x1000
	s_addc_u32 s83, s83, 0
	global_load_dword v74, v156, s[82:83] nt
	s_add_u32 s82, s82, 0x1000
	s_addc_u32 s83, s83, 0
	global_load_dword v75, v156, s[82:83] nt
	s_add_u32 s82, s82, 0x1000
	s_addc_u32 s83, s83, 0
	global_load_dword v76, v156, s[82:83] nt
	s_add_u32 s82, s82, 0x1000
	s_addc_u32 s83, s83, 0
	global_load_dword v77, v156, s[82:83] nt
	s_add_u32 s82, s82, 0x1000
	s_addc_u32 s83, s83, 0
	global_load_dword v78, v156, s[82:83] nt
	s_add_u32 s82, s82, 0x1000
	s_addc_u32 s83, s83, 0
	global_load_dword v79, v156, s[82:83] nt
	s_add_u32 s82, s82, 0x1000
	s_addc_u32 s83, s83, 0
	global_load_dword v80, v156, s[82:83] nt
	s_add_u32 s82, s82, 0x1000
	s_addc_u32 s83, s83, 0
	global_load_dword v81, v156, s[82:83] nt
	s_add_u32 s82, s82, 0x1000
	s_addc_u32 s83, s83, 0
	global_load_dword v82, v156, s[82:83] nt
	s_add_u32 s82, s82, 0x1000
	s_addc_u32 s83, s83, 0
	global_load_dword v83, v156, s[82:83] nt
	s_add_u32 s82, s82, 0x1000
	s_addc_u32 s83, s83, 0
	global_load_dword v84, v156, s[82:83] nt
	s_add_u32 s82, s82, 0x1000
	s_addc_u32 s83, s83, 0
	global_load_dword v85, v156, s[82:83] nt
	s_add_u32 s82, s82, 0x1000
	s_addc_u32 s83, s83, 0
	global_load_dword v86, v156, s[82:83] nt
	s_add_u32 s82, s82, 0x1000
	s_addc_u32 s83, s83, 0
	global_load_dword v87, v156, s[82:83] nt
	s_add_u32 s82, s82, 0x1000
	s_addc_u32 s83, s83, 0
	global_load_dword v88, v156, s[82:83] nt
	s_add_u32 s82, s82, 0x1000
	s_addc_u32 s83, s83, 0
	global_load_dword v89, v156, s[82:83] nt
	s_add_u32 s82, s82, 0x1000
	s_addc_u32 s83, s83, 0
	global_load_dword v90, v156, s[82:83] nt
	s_add_u32 s82, s82, 0x1000
	s_addc_u32 s83, s83, 0
	global_load_dword v91, v156, s[82:83] nt
	s_add_u32 s82, s82, 0x1000
	s_addc_u32 s83, s83, 0
	global_load_dword v92, v156, s[82:83] nt
	s_add_u32 s82, s82, 0x1000
	s_addc_u32 s83, s83, 0
	global_load_dword v93, v156, s[82:83] nt
	s_add_u32 s82, s82, 0x1000
	s_addc_u32 s83, s83, 0
	global_load_dword v94, v156, s[82:83] nt
	s_add_u32 s82, s82, 0x1000
	s_addc_u32 s83, s83, 0
	global_load_dword v95, v156, s[82:83] nt
	s_add_u32 s82, s82, 0x1000
	s_addc_u32 s83, s83, 0
	global_load_dword v96, v156, s[82:83] nt
	s_add_u32 s82, s82, 0x1000
	s_addc_u32 s83, s83, 0
	global_load_dword v97, v156, s[82:83] nt
	s_add_u32 s82, s82, 0x1000
	s_addc_u32 s83, s83, 0
	global_load_dword v98, v156, s[82:83] nt
	s_add_u32 s82, s82, 0x1000
	s_addc_u32 s83, s83, 0
	global_load_dword v99, v156, s[82:83] nt
	s_add_u32 s82, s82, 0x1000
	s_addc_u32 s83, s83, 0
	global_load_dword v100, v156, s[82:83] nt
	s_add_u32 s82, s82, 0x1000
	s_addc_u32 s83, s83, 0
	global_load_dword v101, v156, s[82:83] nt
	s_add_u32 s82, s82, 0x1000
	s_addc_u32 s83, s83, 0
	global_load_dword v102, v156, s[82:83] nt
	s_add_u32 s82, s82, 0x1000
	s_addc_u32 s83, s83, 0
	global_load_dword v103, v156, s[82:83] nt
	s_add_u32 s82, s82, 0x1000
	s_addc_u32 s83, s83, 0
	global_load_dword v104, v156, s[82:83] nt
	s_add_u32 s82, s82, 0x1000
	s_addc_u32 s83, s83, 0
	global_load_dword v105, v156, s[82:83] nt
	s_add_u32 s82, s82, 0x1000
	s_addc_u32 s83, s83, 0
	global_load_dword v106, v156, s[82:83] nt
	s_add_u32 s82, s82, 0x1000
	s_addc_u32 s83, s83, 0
	global_load_dword v107, v156, s[82:83] nt
	s_add_u32 s82, s82, 0x1000
	s_addc_u32 s83, s83, 0
	global_load_dword v108, v156, s[82:83] nt
	s_add_u32 s82, s82, 0x1000
	s_addc_u32 s83, s83, 0
	global_load_dword v109, v156, s[82:83] nt
	s_add_u32 s82, s82, 0x1000
	s_addc_u32 s83, s83, 0
	global_load_dword v110, v156, s[82:83] nt
	s_add_u32 s82, s82, 0x1000
	s_addc_u32 s83, s83, 0
	global_load_dword v111, v156, s[82:83] nt
	s_add_u32 s82, s82, 0x1000
	s_addc_u32 s83, s83, 0
	global_load_dword v112, v156, s[82:83] nt
	s_add_u32 s82, s82, 0x1000
	s_addc_u32 s83, s83, 0
	global_load_dword v113, v156, s[82:83] nt
	s_add_u32 s82, s82, 0x1000
	s_addc_u32 s83, s83, 0
	global_load_dword v114, v156, s[82:83] nt
	s_add_u32 s82, s82, 0x1000
	s_addc_u32 s83, s83, 0
	global_load_dword v115, v156, s[82:83] nt
	s_add_u32 s82, s82, 0x1000
	s_addc_u32 s83, s83, 0
	global_load_dword v116, v156, s[82:83] nt
	s_add_u32 s82, s82, 0x1000
	s_addc_u32 s83, s83, 0
	global_load_dword v117, v156, s[82:83] nt
	s_add_u32 s82, s82, 0x1000
	s_addc_u32 s83, s83, 0
	global_load_dword v118, v156, s[82:83] nt
	s_add_u32 s82, s82, 0x1000
	s_addc_u32 s83, s83, 0
	global_load_dword v119, v156, s[82:83] nt
; __global__ void __launch_bounds__(NTHR, 2) hybrid_fwd(Args args) {
;     ...
;             float a[8];
; #pragma unroll
;             for (int kk = 0; kk < 8; ++kk) a[kk] = 0.f;
; #pragma unroll 8
;             for (int d = 0; d < 128; ++d) { const float wv = w_pool_out[(size_t)(gb + d) * 1024 + n] * pool_scale[gb + d];
; #pragma unroll
;                 for (int kk = 0; kk < 8; ++kk) a[kk] += pool_w[(size_t)(k0 + kk) * 128 + d] * wv; }
	s_add_u32 s82, s82, 0x1000
	s_addc_u32 s83, s83, 0
	global_load_dword v120, v156, s[82:83] nt
	s_add_u32 s82, s82, 0x1000
	s_addc_u32 s83, s83, 0
	global_load_dword v121, v156, s[82:83] nt
	s_add_u32 s82, s82, 0x1000
	s_addc_u32 s83, s83, 0
	global_load_dword v122, v156, s[82:83] nt
	s_add_u32 s82, s82, 0x1000
	s_addc_u32 s83, s83, 0
	global_load_dword v123, v156, s[82:83] nt
	s_add_u32 s82, s82, 0x1000
	s_addc_u32 s83, s83, 0
	global_load_dword v124, v156, s[82:83] nt
	s_add_u32 s82, s82, 0x1000
	s_addc_u32 s83, s83, 0
	global_load_dword v125, v156, s[82:83] nt
	s_add_u32 s82, s82, 0x1000
	s_addc_u32 s83, s83, 0
	global_load_dword v126, v156, s[82:83] nt
	s_add_u32 s82, s82, 0x1000
	s_addc_u32 s83, s83, 0
	global_load_dword v127, v156, s[82:83] nt
	s_lshl_b32 s79, s28, 2
	s_add_u32 s84, s10, s79
	s_addc_u32 s85, s11, 0
	global_load_dword v128, v157, s[84:85]
	global_load_dword v129, v157, s[84:85] offset:256
	s_lshl_b32 s79, s27, 9
	s_add_u32 s84, s8, s79
	s_addc_u32 s85, s9, 0
	global_load_dword v130, v157, s[84:85] offset:0
	global_load_dword v131, v157, s[84:85] offset:256
	global_load_dword v132, v157, s[84:85] offset:512
	global_load_dword v133, v157, s[84:85] offset:768
	global_load_dword v134, v157, s[84:85] offset:1024
	global_load_dword v135, v157, s[84:85] offset:1280
	global_load_dword v136, v157, s[84:85] offset:1536
	global_load_dword v137, v157, s[84:85] offset:1792
	global_load_dword v138, v157, s[84:85] offset:2048
	global_load_dword v139, v157, s[84:85] offset:2304
	global_load_dword v140, v157, s[84:85] offset:2560
	global_load_dword v141, v157, s[84:85] offset:2816
	global_load_dword v142, v157, s[84:85] offset:3072
	global_load_dword v143, v157, s[84:85] offset:3328
	global_load_dword v144, v157, s[84:85] offset:3584
	global_load_dword v145, v157, s[84:85] offset:3840
	v_mov_b32_e32 v146, 0
	v_mov_b32_e32 v147, 0
	v_mov_b32_e32 v148, 0
	v_mov_b32_e32 v149, 0
	v_mov_b32_e32 v150, 0
	v_mov_b32_e32 v151, 0
	v_mov_b32_e32 v152, 0
	v_mov_b32_e32 v153, 0
	s_waitcnt vmcnt(0)
	s_nop 0
	v_readlane_b32 s88, v128, 0
	v_readlane_b32 s77, v130, 0
	v_readlane_b32 s78, v132, 0
	v_readlane_b32 s79, v134, 0
	v_readlane_b32 s80, v136, 0
	v_readlane_b32 s81, v138, 0
	v_readlane_b32 s82, v140, 0
	v_readlane_b32 s83, v142, 0
	v_readlane_b32 s84, v144, 0
	v_mul_f32_e32 v154, s88, v0
	v_fmac_f32_e32 v146, s77, v154
	v_fmac_f32_e32 v147, s78, v154
	v_fmac_f32_e32 v148, s79, v154
	v_fmac_f32_e32 v149, s80, v154
	v_fmac_f32_e32 v150, s81, v154
	v_fmac_f32_e32 v151, s82, v154
	v_fmac_f32_e32 v152, s83, v154
	v_fmac_f32_e32 v153, s84, v154
	v_readlane_b32 s88, v128, 1
	v_readlane_b32 s77, v130, 1
	v_readlane_b32 s78, v132, 1
	v_readlane_b32 s79, v134, 1
	v_readlane_b32 s80, v136, 1
	v_readlane_b32 s81, v138, 1
	v_readlane_b32 s82, v140, 1
	v_readlane_b32 s83, v142, 1
	v_readlane_b32 s84, v144, 1
	v_mul_f32_e32 v154, s88, v1
	v_fmac_f32_e32 v146, s77, v154
	v_fmac_f32_e32 v147, s78, v154
	v_fmac_f32_e32 v148, s79, v154
	v_fmac_f32_e32 v149, s80, v154
	v_fmac_f32_e32 v150, s81, v154
	v_fmac_f32_e32 v151, s82, v154
	v_fmac_f32_e32 v152, s83, v154
	v_fmac_f32_e32 v153, s84, v154
	v_readlane_b32 s88, v128, 2
	v_readlane_b32 s77, v130, 2
	v_readlane_b32 s78, v132, 2
	v_readlane_b32 s79, v134, 2
	v_readlane_b32 s80, v136, 2
	v_readlane_b32 s81, v138, 2
	v_readlane_b32 s82, v140, 2
	v_readlane_b32 s83, v142, 2
	v_readlane_b32 s84, v144, 2
	v_mul_f32_e32 v154, s88, v2
	v_fmac_f32_e32 v146, s77, v154
	v_fmac_f32_e32 v147, s78, v154
	v_fmac_f32_e32 v148, s79, v154
	v_fmac_f32_e32 v149, s80, v154
	v_fmac_f32_e32 v150, s81, v154
	v_fmac_f32_e32 v151, s82, v154
	v_fmac_f32_e32 v152, s83, v154
	v_fmac_f32_e32 v153, s84, v154
	v_readlane_b32 s88, v128, 3
	v_readlane_b32 s77, v130, 3
	v_readlane_b32 s78, v132, 3
	v_readlane_b32 s79, v134, 3
	v_readlane_b32 s80, v136, 3
	v_readlane_b32 s81, v138, 3
	v_readlane_b32 s82, v140, 3
	v_readlane_b32 s83, v142, 3
	v_readlane_b32 s84, v144, 3
	v_mul_f32_e32 v154, s88, v3
	v_fmac_f32_e32 v146, s77, v154
	v_fmac_f32_e32 v147, s78, v154
	v_fmac_f32_e32 v148, s79, v154
	v_fmac_f32_e32 v149, s80, v154
	v_fmac_f32_e32 v150, s81, v154
	v_fmac_f32_e32 v151, s82, v154
	v_fmac_f32_e32 v152, s83, v154
	v_fmac_f32_e32 v153, s84, v154
	v_readlane_b32 s88, v128, 4
	v_readlane_b32 s77, v130, 4
	v_readlane_b32 s78, v132, 4
	v_readlane_b32 s79, v134, 4
	v_readlane_b32 s80, v136, 4
	v_readlane_b32 s81, v138, 4
	v_readlane_b32 s82, v140, 4
	v_readlane_b32 s83, v142, 4
	v_readlane_b32 s84, v144, 4
	v_mul_f32_e32 v154, s88, v4
	v_fmac_f32_e32 v146, s77, v154
	v_fmac_f32_e32 v147, s78, v154
	v_fmac_f32_e32 v148, s79, v154
	v_fmac_f32_e32 v149, s80, v154
	v_fmac_f32_e32 v150, s81, v154
	v_fmac_f32_e32 v151, s82, v154
	v_fmac_f32_e32 v152, s83, v154
	v_fmac_f32_e32 v153, s84, v154
	v_readlane_b32 s88, v128, 5
	v_readlane_b32 s77, v130, 5
	v_readlane_b32 s78, v132, 5
	v_readlane_b32 s79, v134, 5
	v_readlane_b32 s80, v136, 5
	v_readlane_b32 s81, v138, 5
	v_readlane_b32 s82, v140, 5
	v_readlane_b32 s83, v142, 5
	v_readlane_b32 s84, v144, 5
	v_mul_f32_e32 v154, s88, v5
	v_fmac_f32_e32 v146, s77, v154
	v_fmac_f32_e32 v147, s78, v154
	v_fmac_f32_e32 v148, s79, v154
	v_fmac_f32_e32 v149, s80, v154
	v_fmac_f32_e32 v150, s81, v154
	v_fmac_f32_e32 v151, s82, v154
	v_fmac_f32_e32 v152, s83, v154
	v_fmac_f32_e32 v153, s84, v154
	v_readlane_b32 s88, v128, 6
	v_readlane_b32 s77, v130, 6
	v_readlane_b32 s78, v132, 6
	v_readlane_b32 s79, v134, 6
	v_readlane_b32 s80, v136, 6
	v_readlane_b32 s81, v138, 6
	v_readlane_b32 s82, v140, 6
	v_readlane_b32 s83, v142, 6
	v_readlane_b32 s84, v144, 6
	v_mul_f32_e32 v154, s88, v6
	v_fmac_f32_e32 v146, s77, v154
; __global__ void __launch_bounds__(NTHR, 2) hybrid_fwd(Args args) {
;     ...
;             for (int d = 0; d < 128; ++d) { const float wv = w_pool_out[(size_t)(gb + d) * 1024 + n] * pool_scale[gb + d];
; #pragma unroll
;                 for (int kk = 0; kk < 8; ++kk) a[kk] += pool_w[(size_t)(k0 + kk) * 128 + d] * wv; }
	v_fmac_f32_e32 v147, s78, v154
	v_fmac_f32_e32 v148, s79, v154
	v_fmac_f32_e32 v149, s80, v154
	v_fmac_f32_e32 v150, s81, v154
	v_fmac_f32_e32 v151, s82, v154
	v_fmac_f32_e32 v152, s83, v154
	v_fmac_f32_e32 v153, s84, v154
	v_readlane_b32 s88, v128, 7
	v_readlane_b32 s77, v130, 7
	v_readlane_b32 s78, v132, 7
	v_readlane_b32 s79, v134, 7
	v_readlane_b32 s80, v136, 7
	v_readlane_b32 s81, v138, 7
	v_readlane_b32 s82, v140, 7
	v_readlane_b32 s83, v142, 7
	v_readlane_b32 s84, v144, 7
	v_mul_f32_e32 v154, s88, v7
	v_fmac_f32_e32 v146, s77, v154
	v_fmac_f32_e32 v147, s78, v154
	v_fmac_f32_e32 v148, s79, v154
	v_fmac_f32_e32 v149, s80, v154
	v_fmac_f32_e32 v150, s81, v154
	v_fmac_f32_e32 v151, s82, v154
	v_fmac_f32_e32 v152, s83, v154
	v_fmac_f32_e32 v153, s84, v154
	v_readlane_b32 s88, v128, 8
	v_readlane_b32 s77, v130, 8
	v_readlane_b32 s78, v132, 8
	v_readlane_b32 s79, v134, 8
	v_readlane_b32 s80, v136, 8
	v_readlane_b32 s81, v138, 8
	v_readlane_b32 s82, v140, 8
	v_readlane_b32 s83, v142, 8
	v_readlane_b32 s84, v144, 8
	v_mul_f32_e32 v154, s88, v8
	v_fmac_f32_e32 v146, s77, v154
	v_fmac_f32_e32 v147, s78, v154
	v_fmac_f32_e32 v148, s79, v154
	v_fmac_f32_e32 v149, s80, v154
	v_fmac_f32_e32 v150, s81, v154
	v_fmac_f32_e32 v151, s82, v154
	v_fmac_f32_e32 v152, s83, v154
	v_fmac_f32_e32 v153, s84, v154
	v_readlane_b32 s88, v128, 9
	v_readlane_b32 s77, v130, 9
	v_readlane_b32 s78, v132, 9
	v_readlane_b32 s79, v134, 9
	v_readlane_b32 s80, v136, 9
	v_readlane_b32 s81, v138, 9
	v_readlane_b32 s82, v140, 9
	v_readlane_b32 s83, v142, 9
	v_readlane_b32 s84, v144, 9
	v_mul_f32_e32 v154, s88, v9
	v_fmac_f32_e32 v146, s77, v154
	v_fmac_f32_e32 v147, s78, v154
	v_fmac_f32_e32 v148, s79, v154
	v_fmac_f32_e32 v149, s80, v154
	v_fmac_f32_e32 v150, s81, v154
	v_fmac_f32_e32 v151, s82, v154
	v_fmac_f32_e32 v152, s83, v154
	v_fmac_f32_e32 v153, s84, v154
	v_readlane_b32 s88, v128, 10
	v_readlane_b32 s77, v130, 10
	v_readlane_b32 s78, v132, 10
	v_readlane_b32 s79, v134, 10
	v_readlane_b32 s80, v136, 10
	v_readlane_b32 s81, v138, 10
	v_readlane_b32 s82, v140, 10
	v_readlane_b32 s83, v142, 10
	v_readlane_b32 s84, v144, 10
	v_mul_f32_e32 v154, s88, v10
	v_fmac_f32_e32 v146, s77, v154
	v_fmac_f32_e32 v147, s78, v154
	v_fmac_f32_e32 v148, s79, v154
	v_fmac_f32_e32 v149, s80, v154
	v_fmac_f32_e32 v150, s81, v154
	v_fmac_f32_e32 v151, s82, v154
	v_fmac_f32_e32 v152, s83, v154
	v_fmac_f32_e32 v153, s84, v154
	v_readlane_b32 s88, v128, 11
	v_readlane_b32 s77, v130, 11
	v_readlane_b32 s78, v132, 11
	v_readlane_b32 s79, v134, 11
	v_readlane_b32 s80, v136, 11
	v_readlane_b32 s81, v138, 11
	v_readlane_b32 s82, v140, 11
	v_readlane_b32 s83, v142, 11
	v_readlane_b32 s84, v144, 11
	v_mul_f32_e32 v154, s88, v11
	v_fmac_f32_e32 v146, s77, v154
	v_fmac_f32_e32 v147, s78, v154
	v_fmac_f32_e32 v148, s79, v154
	v_fmac_f32_e32 v149, s80, v154
	v_fmac_f32_e32 v150, s81, v154
	v_fmac_f32_e32 v151, s82, v154
	v_fmac_f32_e32 v152, s83, v154
	v_fmac_f32_e32 v153, s84, v154
	v_readlane_b32 s88, v128, 12
	v_readlane_b32 s77, v130, 12
	v_readlane_b32 s78, v132, 12
	v_readlane_b32 s79, v134, 12
	v_readlane_b32 s80, v136, 12
	v_readlane_b32 s81, v138, 12
	v_readlane_b32 s82, v140, 12
	v_readlane_b32 s83, v142, 12
	v_readlane_b32 s84, v144, 12
	v_mul_f32_e32 v154, s88, v12
	v_fmac_f32_e32 v146, s77, v154
	v_fmac_f32_e32 v147, s78, v154
	v_fmac_f32_e32 v148, s79, v154
	v_fmac_f32_e32 v149, s80, v154
	v_fmac_f32_e32 v150, s81, v154
	v_fmac_f32_e32 v151, s82, v154
	v_fmac_f32_e32 v152, s83, v154
	v_fmac_f32_e32 v153, s84, v154
	v_readlane_b32 s88, v128, 13
	v_readlane_b32 s77, v130, 13
	v_readlane_b32 s78, v132, 13
	v_readlane_b32 s79, v134, 13
	v_readlane_b32 s80, v136, 13
	v_readlane_b32 s81, v138, 13
	v_readlane_b32 s82, v140, 13
	v_readlane_b32 s83, v142, 13
	v_readlane_b32 s84, v144, 13
	v_mul_f32_e32 v154, s88, v13
	v_fmac_f32_e32 v146, s77, v154
	v_fmac_f32_e32 v147, s78, v154
	v_fmac_f32_e32 v148, s79, v154
	v_fmac_f32_e32 v149, s80, v154
	v_fmac_f32_e32 v150, s81, v154
	v_fmac_f32_e32 v151, s82, v154
	v_fmac_f32_e32 v152, s83, v154
	v_fmac_f32_e32 v153, s84, v154
	v_readlane_b32 s88, v128, 14
	v_readlane_b32 s77, v130, 14
	v_readlane_b32 s78, v132, 14
	v_readlane_b32 s79, v134, 14
	v_readlane_b32 s80, v136, 14
	v_readlane_b32 s81, v138, 14
	v_readlane_b32 s82, v140, 14
	v_readlane_b32 s83, v142, 14
	v_readlane_b32 s84, v144, 14
	v_mul_f32_e32 v154, s88, v14
	v_fmac_f32_e32 v146, s77, v154
	v_fmac_f32_e32 v147, s78, v154
	v_fmac_f32_e32 v148, s79, v154
	v_fmac_f32_e32 v149, s80, v154
	v_fmac_f32_e32 v150, s81, v154
	v_fmac_f32_e32 v151, s82, v154
	v_fmac_f32_e32 v152, s83, v154
	v_fmac_f32_e32 v153, s84, v154
	v_readlane_b32 s88, v128, 15
	v_readlane_b32 s77, v130, 15
	v_readlane_b32 s78, v132, 15
	v_readlane_b32 s79, v134, 15
	v_readlane_b32 s80, v136, 15
	v_readlane_b32 s81, v138, 15
	v_readlane_b32 s82, v140, 15
	v_readlane_b32 s83, v142, 15
	v_readlane_b32 s84, v144, 15
	v_mul_f32_e32 v154, s88, v15
	v_fmac_f32_e32 v146, s77, v154
	v_fmac_f32_e32 v147, s78, v154
	v_fmac_f32_e32 v148, s79, v154
	v_fmac_f32_e32 v149, s80, v154
	v_fmac_f32_e32 v150, s81, v154
	v_fmac_f32_e32 v151, s82, v154
	v_fmac_f32_e32 v152, s83, v154
	v_fmac_f32_e32 v153, s84, v154
	v_readlane_b32 s88, v128, 16
	v_readlane_b32 s77, v130, 16
	v_readlane_b32 s78, v132, 16
	v_readlane_b32 s79, v134, 16
	v_readlane_b32 s80, v136, 16
	v_readlane_b32 s81, v138, 16
	v_readlane_b32 s82, v140, 16
	v_readlane_b32 s83, v142, 16
	v_readlane_b32 s84, v144, 16
	v_mul_f32_e32 v154, s88, v16
	v_fmac_f32_e32 v146, s77, v154
	v_fmac_f32_e32 v147, s78, v154
	v_fmac_f32_e32 v148, s79, v154
	v_fmac_f32_e32 v149, s80, v154
; __global__ void __launch_bounds__(NTHR, 2) hybrid_fwd(Args args) {
;     ...
;             for (int d = 0; d < 128; ++d) { const float wv = w_pool_out[(size_t)(gb + d) * 1024 + n] * pool_scale[gb + d];
; #pragma unroll
;                 for (int kk = 0; kk < 8; ++kk) a[kk] += pool_w[(size_t)(k0 + kk) * 128 + d] * wv; }
	v_fmac_f32_e32 v150, s81, v154
	v_fmac_f32_e32 v151, s82, v154
	v_fmac_f32_e32 v152, s83, v154
	v_fmac_f32_e32 v153, s84, v154
	v_readlane_b32 s88, v128, 17
	v_readlane_b32 s77, v130, 17
	v_readlane_b32 s78, v132, 17
	v_readlane_b32 s79, v134, 17
	v_readlane_b32 s80, v136, 17
	v_readlane_b32 s81, v138, 17
	v_readlane_b32 s82, v140, 17
	v_readlane_b32 s83, v142, 17
	v_readlane_b32 s84, v144, 17
	v_mul_f32_e32 v154, s88, v17
	v_fmac_f32_e32 v146, s77, v154
	v_fmac_f32_e32 v147, s78, v154
	v_fmac_f32_e32 v148, s79, v154
	v_fmac_f32_e32 v149, s80, v154
	v_fmac_f32_e32 v150, s81, v154
	v_fmac_f32_e32 v151, s82, v154
	v_fmac_f32_e32 v152, s83, v154
	v_fmac_f32_e32 v153, s84, v154
	v_readlane_b32 s88, v128, 18
	v_readlane_b32 s77, v130, 18
	v_readlane_b32 s78, v132, 18
	v_readlane_b32 s79, v134, 18
	v_readlane_b32 s80, v136, 18
	v_readlane_b32 s81, v138, 18
	v_readlane_b32 s82, v140, 18
	v_readlane_b32 s83, v142, 18
	v_readlane_b32 s84, v144, 18
	v_mul_f32_e32 v154, s88, v18
	v_fmac_f32_e32 v146, s77, v154
	v_fmac_f32_e32 v147, s78, v154
	v_fmac_f32_e32 v148, s79, v154
	v_fmac_f32_e32 v149, s80, v154
	v_fmac_f32_e32 v150, s81, v154
	v_fmac_f32_e32 v151, s82, v154
	v_fmac_f32_e32 v152, s83, v154
	v_fmac_f32_e32 v153, s84, v154
	v_readlane_b32 s88, v128, 19
	v_readlane_b32 s77, v130, 19
	v_readlane_b32 s78, v132, 19
	v_readlane_b32 s79, v134, 19
	v_readlane_b32 s80, v136, 19
	v_readlane_b32 s81, v138, 19
	v_readlane_b32 s82, v140, 19
	v_readlane_b32 s83, v142, 19
	v_readlane_b32 s84, v144, 19
	v_mul_f32_e32 v154, s88, v19
	v_fmac_f32_e32 v146, s77, v154
	v_fmac_f32_e32 v147, s78, v154
	v_fmac_f32_e32 v148, s79, v154
	v_fmac_f32_e32 v149, s80, v154
	v_fmac_f32_e32 v150, s81, v154
	v_fmac_f32_e32 v151, s82, v154
	v_fmac_f32_e32 v152, s83, v154
	v_fmac_f32_e32 v153, s84, v154
	v_readlane_b32 s88, v128, 20
	v_readlane_b32 s77, v130, 20
	v_readlane_b32 s78, v132, 20
	v_readlane_b32 s79, v134, 20
	v_readlane_b32 s80, v136, 20
	v_readlane_b32 s81, v138, 20
	v_readlane_b32 s82, v140, 20
	v_readlane_b32 s83, v142, 20
	v_readlane_b32 s84, v144, 20
	v_mul_f32_e32 v154, s88, v20
	v_fmac_f32_e32 v146, s77, v154
	v_fmac_f32_e32 v147, s78, v154
	v_fmac_f32_e32 v148, s79, v154
	v_fmac_f32_e32 v149, s80, v154
	v_fmac_f32_e32 v150, s81, v154
	v_fmac_f32_e32 v151, s82, v154
	v_fmac_f32_e32 v152, s83, v154
	v_fmac_f32_e32 v153, s84, v154
	v_readlane_b32 s88, v128, 21
	v_readlane_b32 s77, v130, 21
	v_readlane_b32 s78, v132, 21
	v_readlane_b32 s79, v134, 21
	v_readlane_b32 s80, v136, 21
	v_readlane_b32 s81, v138, 21
	v_readlane_b32 s82, v140, 21
	v_readlane_b32 s83, v142, 21
	v_readlane_b32 s84, v144, 21
	v_mul_f32_e32 v154, s88, v21
	v_fmac_f32_e32 v146, s77, v154
	v_fmac_f32_e32 v147, s78, v154
	v_fmac_f32_e32 v148, s79, v154
	v_fmac_f32_e32 v149, s80, v154
	v_fmac_f32_e32 v150, s81, v154
	v_fmac_f32_e32 v151, s82, v154
	v_fmac_f32_e32 v152, s83, v154
	v_fmac_f32_e32 v153, s84, v154
	v_readlane_b32 s88, v128, 22
	v_readlane_b32 s77, v130, 22
	v_readlane_b32 s78, v132, 22
	v_readlane_b32 s79, v134, 22
	v_readlane_b32 s80, v136, 22
	v_readlane_b32 s81, v138, 22
	v_readlane_b32 s82, v140, 22
	v_readlane_b32 s83, v142, 22
	v_readlane_b32 s84, v144, 22
	v_mul_f32_e32 v154, s88, v22
	v_fmac_f32_e32 v146, s77, v154
	v_fmac_f32_e32 v147, s78, v154
	v_fmac_f32_e32 v148, s79, v154
	v_fmac_f32_e32 v149, s80, v154
	v_fmac_f32_e32 v150, s81, v154
	v_fmac_f32_e32 v151, s82, v154
	v_fmac_f32_e32 v152, s83, v154
	v_fmac_f32_e32 v153, s84, v154
	v_readlane_b32 s88, v128, 23
	v_readlane_b32 s77, v130, 23
	v_readlane_b32 s78, v132, 23
	v_readlane_b32 s79, v134, 23
	v_readlane_b32 s80, v136, 23
	v_readlane_b32 s81, v138, 23
	v_readlane_b32 s82, v140, 23
	v_readlane_b32 s83, v142, 23
	v_readlane_b32 s84, v144, 23
	v_mul_f32_e32 v154, s88, v23
	v_fmac_f32_e32 v146, s77, v154
	v_fmac_f32_e32 v147, s78, v154
	v_fmac_f32_e32 v148, s79, v154
	v_fmac_f32_e32 v149, s80, v154
	v_fmac_f32_e32 v150, s81, v154
	v_fmac_f32_e32 v151, s82, v154
	v_fmac_f32_e32 v152, s83, v154
	v_fmac_f32_e32 v153, s84, v154
	v_readlane_b32 s88, v128, 24
	v_readlane_b32 s77, v130, 24
	v_readlane_b32 s78, v132, 24
	v_readlane_b32 s79, v134, 24
	v_readlane_b32 s80, v136, 24
	v_readlane_b32 s81, v138, 24
	v_readlane_b32 s82, v140, 24
	v_readlane_b32 s83, v142, 24
	v_readlane_b32 s84, v144, 24
	v_mul_f32_e32 v154, s88, v24
	v_fmac_f32_e32 v146, s77, v154
	v_fmac_f32_e32 v147, s78, v154
	v_fmac_f32_e32 v148, s79, v154
	v_fmac_f32_e32 v149, s80, v154
	v_fmac_f32_e32 v150, s81, v154
	v_fmac_f32_e32 v151, s82, v154
	v_fmac_f32_e32 v152, s83, v154
	v_fmac_f32_e32 v153, s84, v154
	v_readlane_b32 s88, v128, 25
	v_readlane_b32 s77, v130, 25
	v_readlane_b32 s78, v132, 25
	v_readlane_b32 s79, v134, 25
	v_readlane_b32 s80, v136, 25
	v_readlane_b32 s81, v138, 25
	v_readlane_b32 s82, v140, 25
	v_readlane_b32 s83, v142, 25
	v_readlane_b32 s84, v144, 25
	v_mul_f32_e32 v154, s88, v25
	v_fmac_f32_e32 v146, s77, v154
	v_fmac_f32_e32 v147, s78, v154
	v_fmac_f32_e32 v148, s79, v154
	v_fmac_f32_e32 v149, s80, v154
	v_fmac_f32_e32 v150, s81, v154
	v_fmac_f32_e32 v151, s82, v154
	v_fmac_f32_e32 v152, s83, v154
	v_fmac_f32_e32 v153, s84, v154
	v_readlane_b32 s88, v128, 26
	v_readlane_b32 s77, v130, 26
	v_readlane_b32 s78, v132, 26
	v_readlane_b32 s79, v134, 26
	v_readlane_b32 s80, v136, 26
	v_readlane_b32 s81, v138, 26
	v_readlane_b32 s82, v140, 26
	v_readlane_b32 s83, v142, 26
	v_readlane_b32 s84, v144, 26
	v_mul_f32_e32 v154, s88, v26
	v_fmac_f32_e32 v146, s77, v154
	v_fmac_f32_e32 v147, s78, v154
	v_fmac_f32_e32 v148, s79, v154
	v_fmac_f32_e32 v149, s80, v154
	v_fmac_f32_e32 v150, s81, v154
	v_fmac_f32_e32 v151, s82, v154
; __global__ void __launch_bounds__(NTHR, 2) hybrid_fwd(Args args) {
;     ...
;             for (int d = 0; d < 128; ++d) { const float wv = w_pool_out[(size_t)(gb + d) * 1024 + n] * pool_scale[gb + d];
; #pragma unroll
;                 for (int kk = 0; kk < 8; ++kk) a[kk] += pool_w[(size_t)(k0 + kk) * 128 + d] * wv; }
	v_fmac_f32_e32 v152, s83, v154
	v_fmac_f32_e32 v153, s84, v154
	v_readlane_b32 s88, v128, 27
	v_readlane_b32 s77, v130, 27
	v_readlane_b32 s78, v132, 27
	v_readlane_b32 s79, v134, 27
	v_readlane_b32 s80, v136, 27
	v_readlane_b32 s81, v138, 27
	v_readlane_b32 s82, v140, 27
	v_readlane_b32 s83, v142, 27
	v_readlane_b32 s84, v144, 27
	v_mul_f32_e32 v154, s88, v27
	v_fmac_f32_e32 v146, s77, v154
	v_fmac_f32_e32 v147, s78, v154
	v_fmac_f32_e32 v148, s79, v154
	v_fmac_f32_e32 v149, s80, v154
	v_fmac_f32_e32 v150, s81, v154
	v_fmac_f32_e32 v151, s82, v154
	v_fmac_f32_e32 v152, s83, v154
	v_fmac_f32_e32 v153, s84, v154
	v_readlane_b32 s88, v128, 28
	v_readlane_b32 s77, v130, 28
	v_readlane_b32 s78, v132, 28
	v_readlane_b32 s79, v134, 28
	v_readlane_b32 s80, v136, 28
	v_readlane_b32 s81, v138, 28
	v_readlane_b32 s82, v140, 28
	v_readlane_b32 s83, v142, 28
	v_readlane_b32 s84, v144, 28
	v_mul_f32_e32 v154, s88, v28
	v_fmac_f32_e32 v146, s77, v154
	v_fmac_f32_e32 v147, s78, v154
	v_fmac_f32_e32 v148, s79, v154
	v_fmac_f32_e32 v149, s80, v154
	v_fmac_f32_e32 v150, s81, v154
	v_fmac_f32_e32 v151, s82, v154
	v_fmac_f32_e32 v152, s83, v154
	v_fmac_f32_e32 v153, s84, v154
	v_readlane_b32 s88, v128, 29
	v_readlane_b32 s77, v130, 29
	v_readlane_b32 s78, v132, 29
	v_readlane_b32 s79, v134, 29
	v_readlane_b32 s80, v136, 29
	v_readlane_b32 s81, v138, 29
	v_readlane_b32 s82, v140, 29
	v_readlane_b32 s83, v142, 29
	v_readlane_b32 s84, v144, 29
	v_mul_f32_e32 v154, s88, v29
	v_fmac_f32_e32 v146, s77, v154
	v_fmac_f32_e32 v147, s78, v154
	v_fmac_f32_e32 v148, s79, v154
	v_fmac_f32_e32 v149, s80, v154
	v_fmac_f32_e32 v150, s81, v154
	v_fmac_f32_e32 v151, s82, v154
	v_fmac_f32_e32 v152, s83, v154
	v_fmac_f32_e32 v153, s84, v154
	v_readlane_b32 s88, v128, 30
	v_readlane_b32 s77, v130, 30
	v_readlane_b32 s78, v132, 30
	v_readlane_b32 s79, v134, 30
	v_readlane_b32 s80, v136, 30
	v_readlane_b32 s81, v138, 30
	v_readlane_b32 s82, v140, 30
	v_readlane_b32 s83, v142, 30
	v_readlane_b32 s84, v144, 30
	v_mul_f32_e32 v154, s88, v30
	v_fmac_f32_e32 v146, s77, v154
	v_fmac_f32_e32 v147, s78, v154
	v_fmac_f32_e32 v148, s79, v154
	v_fmac_f32_e32 v149, s80, v154
	v_fmac_f32_e32 v150, s81, v154
	v_fmac_f32_e32 v151, s82, v154
	v_fmac_f32_e32 v152, s83, v154
	v_fmac_f32_e32 v153, s84, v154
	v_readlane_b32 s88, v128, 31
	v_readlane_b32 s77, v130, 31
	v_readlane_b32 s78, v132, 31
	v_readlane_b32 s79, v134, 31
	v_readlane_b32 s80, v136, 31
	v_readlane_b32 s81, v138, 31
	v_readlane_b32 s82, v140, 31
	v_readlane_b32 s83, v142, 31
	v_readlane_b32 s84, v144, 31
	v_mul_f32_e32 v154, s88, v31
	v_fmac_f32_e32 v146, s77, v154
	v_fmac_f32_e32 v147, s78, v154
	v_fmac_f32_e32 v148, s79, v154
	v_fmac_f32_e32 v149, s80, v154
	v_fmac_f32_e32 v150, s81, v154
	v_fmac_f32_e32 v151, s82, v154
	v_fmac_f32_e32 v152, s83, v154
	v_fmac_f32_e32 v153, s84, v154
	v_readlane_b32 s88, v128, 32
	v_readlane_b32 s77, v130, 32
	v_readlane_b32 s78, v132, 32
	v_readlane_b32 s79, v134, 32
	v_readlane_b32 s80, v136, 32
	v_readlane_b32 s81, v138, 32
	v_readlane_b32 s82, v140, 32
	v_readlane_b32 s83, v142, 32
	v_readlane_b32 s84, v144, 32
	v_mul_f32_e32 v154, s88, v32
	v_fmac_f32_e32 v146, s77, v154
	v_fmac_f32_e32 v147, s78, v154
	v_fmac_f32_e32 v148, s79, v154
	v_fmac_f32_e32 v149, s80, v154
	v_fmac_f32_e32 v150, s81, v154
	v_fmac_f32_e32 v151, s82, v154
	v_fmac_f32_e32 v152, s83, v154
	v_fmac_f32_e32 v153, s84, v154
	v_readlane_b32 s88, v128, 33
	v_readlane_b32 s77, v130, 33
	v_readlane_b32 s78, v132, 33
	v_readlane_b32 s79, v134, 33
	v_readlane_b32 s80, v136, 33
	v_readlane_b32 s81, v138, 33
	v_readlane_b32 s82, v140, 33
	v_readlane_b32 s83, v142, 33
	v_readlane_b32 s84, v144, 33
	v_mul_f32_e32 v154, s88, v33
	v_fmac_f32_e32 v146, s77, v154
	v_fmac_f32_e32 v147, s78, v154
	v_fmac_f32_e32 v148, s79, v154
	v_fmac_f32_e32 v149, s80, v154
	v_fmac_f32_e32 v150, s81, v154
	v_fmac_f32_e32 v151, s82, v154
	v_fmac_f32_e32 v152, s83, v154
	v_fmac_f32_e32 v153, s84, v154
	v_readlane_b32 s88, v128, 34
	v_readlane_b32 s77, v130, 34
	v_readlane_b32 s78, v132, 34
	v_readlane_b32 s79, v134, 34
	v_readlane_b32 s80, v136, 34
	v_readlane_b32 s81, v138, 34
	v_readlane_b32 s82, v140, 34
	v_readlane_b32 s83, v142, 34
	v_readlane_b32 s84, v144, 34
	v_mul_f32_e32 v154, s88, v34
	v_fmac_f32_e32 v146, s77, v154
	v_fmac_f32_e32 v147, s78, v154
	v_fmac_f32_e32 v148, s79, v154
	v_fmac_f32_e32 v149, s80, v154
	v_fmac_f32_e32 v150, s81, v154
	v_fmac_f32_e32 v151, s82, v154
	v_fmac_f32_e32 v152, s83, v154
	v_fmac_f32_e32 v153, s84, v154
	v_readlane_b32 s88, v128, 35
	v_readlane_b32 s77, v130, 35
	v_readlane_b32 s78, v132, 35
	v_readlane_b32 s79, v134, 35
	v_readlane_b32 s80, v136, 35
	v_readlane_b32 s81, v138, 35
	v_readlane_b32 s82, v140, 35
	v_readlane_b32 s83, v142, 35
	v_readlane_b32 s84, v144, 35
	v_mul_f32_e32 v154, s88, v35
	v_fmac_f32_e32 v146, s77, v154
	v_fmac_f32_e32 v147, s78, v154
	v_fmac_f32_e32 v148, s79, v154
	v_fmac_f32_e32 v149, s80, v154
	v_fmac_f32_e32 v150, s81, v154
	v_fmac_f32_e32 v151, s82, v154
	v_fmac_f32_e32 v152, s83, v154
	v_fmac_f32_e32 v153, s84, v154
	v_readlane_b32 s88, v128, 36
	v_readlane_b32 s77, v130, 36
	v_readlane_b32 s78, v132, 36
	v_readlane_b32 s79, v134, 36
	v_readlane_b32 s80, v136, 36
	v_readlane_b32 s81, v138, 36
	v_readlane_b32 s82, v140, 36
	v_readlane_b32 s83, v142, 36
	v_readlane_b32 s84, v144, 36
	v_mul_f32_e32 v154, s88, v36
	v_fmac_f32_e32 v146, s77, v154
	v_fmac_f32_e32 v147, s78, v154
	v_fmac_f32_e32 v148, s79, v154
	v_fmac_f32_e32 v149, s80, v154
	v_fmac_f32_e32 v150, s81, v154
	v_fmac_f32_e32 v151, s82, v154
	v_fmac_f32_e32 v152, s83, v154
	v_fmac_f32_e32 v153, s84, v154
	v_readlane_b32 s88, v128, 37
; __global__ void __launch_bounds__(NTHR, 2) hybrid_fwd(Args args) {
;     ...
;             for (int d = 0; d < 128; ++d) { const float wv = w_pool_out[(size_t)(gb + d) * 1024 + n] * pool_scale[gb + d];
; #pragma unroll
;                 for (int kk = 0; kk < 8; ++kk) a[kk] += pool_w[(size_t)(k0 + kk) * 128 + d] * wv; }
	v_readlane_b32 s77, v130, 37
	v_readlane_b32 s78, v132, 37
	v_readlane_b32 s79, v134, 37
	v_readlane_b32 s80, v136, 37
	v_readlane_b32 s81, v138, 37
	v_readlane_b32 s82, v140, 37
	v_readlane_b32 s83, v142, 37
	v_readlane_b32 s84, v144, 37
	v_mul_f32_e32 v154, s88, v37
	v_fmac_f32_e32 v146, s77, v154
	v_fmac_f32_e32 v147, s78, v154
	v_fmac_f32_e32 v148, s79, v154
	v_fmac_f32_e32 v149, s80, v154
	v_fmac_f32_e32 v150, s81, v154
	v_fmac_f32_e32 v151, s82, v154
	v_fmac_f32_e32 v152, s83, v154
	v_fmac_f32_e32 v153, s84, v154
	v_readlane_b32 s88, v128, 38
	v_readlane_b32 s77, v130, 38
	v_readlane_b32 s78, v132, 38
	v_readlane_b32 s79, v134, 38
	v_readlane_b32 s80, v136, 38
	v_readlane_b32 s81, v138, 38
	v_readlane_b32 s82, v140, 38
	v_readlane_b32 s83, v142, 38
	v_readlane_b32 s84, v144, 38
	v_mul_f32_e32 v154, s88, v38
	v_fmac_f32_e32 v146, s77, v154
	v_fmac_f32_e32 v147, s78, v154
	v_fmac_f32_e32 v148, s79, v154
	v_fmac_f32_e32 v149, s80, v154
	v_fmac_f32_e32 v150, s81, v154
	v_fmac_f32_e32 v151, s82, v154
	v_fmac_f32_e32 v152, s83, v154
	v_fmac_f32_e32 v153, s84, v154
	v_readlane_b32 s88, v128, 39
	v_readlane_b32 s77, v130, 39
	v_readlane_b32 s78, v132, 39
	v_readlane_b32 s79, v134, 39
	v_readlane_b32 s80, v136, 39
	v_readlane_b32 s81, v138, 39
	v_readlane_b32 s82, v140, 39
	v_readlane_b32 s83, v142, 39
	v_readlane_b32 s84, v144, 39
	v_mul_f32_e32 v154, s88, v39
	v_fmac_f32_e32 v146, s77, v154
	v_fmac_f32_e32 v147, s78, v154
	v_fmac_f32_e32 v148, s79, v154
	v_fmac_f32_e32 v149, s80, v154
	v_fmac_f32_e32 v150, s81, v154
	v_fmac_f32_e32 v151, s82, v154
	v_fmac_f32_e32 v152, s83, v154
	v_fmac_f32_e32 v153, s84, v154
	v_readlane_b32 s88, v128, 40
	v_readlane_b32 s77, v130, 40
	v_readlane_b32 s78, v132, 40
	v_readlane_b32 s79, v134, 40
	v_readlane_b32 s80, v136, 40
	v_readlane_b32 s81, v138, 40
	v_readlane_b32 s82, v140, 40
	v_readlane_b32 s83, v142, 40
	v_readlane_b32 s84, v144, 40
	v_mul_f32_e32 v154, s88, v40
	v_fmac_f32_e32 v146, s77, v154
	v_fmac_f32_e32 v147, s78, v154
	v_fmac_f32_e32 v148, s79, v154
	v_fmac_f32_e32 v149, s80, v154
	v_fmac_f32_e32 v150, s81, v154
	v_fmac_f32_e32 v151, s82, v154
	v_fmac_f32_e32 v152, s83, v154
	v_fmac_f32_e32 v153, s84, v154
	v_readlane_b32 s88, v128, 41
	v_readlane_b32 s77, v130, 41
	v_readlane_b32 s78, v132, 41
	v_readlane_b32 s79, v134, 41
	v_readlane_b32 s80, v136, 41
	v_readlane_b32 s81, v138, 41
	v_readlane_b32 s82, v140, 41
	v_readlane_b32 s83, v142, 41
	v_readlane_b32 s84, v144, 41
	v_mul_f32_e32 v154, s88, v41
	v_fmac_f32_e32 v146, s77, v154
	v_fmac_f32_e32 v147, s78, v154
	v_fmac_f32_e32 v148, s79, v154
	v_fmac_f32_e32 v149, s80, v154
	v_fmac_f32_e32 v150, s81, v154
	v_fmac_f32_e32 v151, s82, v154
	v_fmac_f32_e32 v152, s83, v154
	v_fmac_f32_e32 v153, s84, v154
	v_readlane_b32 s88, v128, 42
	v_readlane_b32 s77, v130, 42
	v_readlane_b32 s78, v132, 42
	v_readlane_b32 s79, v134, 42
	v_readlane_b32 s80, v136, 42
	v_readlane_b32 s81, v138, 42
	v_readlane_b32 s82, v140, 42
	v_readlane_b32 s83, v142, 42
	v_readlane_b32 s84, v144, 42
	v_mul_f32_e32 v154, s88, v42
	v_fmac_f32_e32 v146, s77, v154
	v_fmac_f32_e32 v147, s78, v154
	v_fmac_f32_e32 v148, s79, v154
	v_fmac_f32_e32 v149, s80, v154
	v_fmac_f32_e32 v150, s81, v154
	v_fmac_f32_e32 v151, s82, v154
	v_fmac_f32_e32 v152, s83, v154
	v_fmac_f32_e32 v153, s84, v154
	v_readlane_b32 s88, v128, 43
	v_readlane_b32 s77, v130, 43
	v_readlane_b32 s78, v132, 43
	v_readlane_b32 s79, v134, 43
	v_readlane_b32 s80, v136, 43
	v_readlane_b32 s81, v138, 43
	v_readlane_b32 s82, v140, 43
	v_readlane_b32 s83, v142, 43
	v_readlane_b32 s84, v144, 43
	v_mul_f32_e32 v154, s88, v43
	v_fmac_f32_e32 v146, s77, v154
	v_fmac_f32_e32 v147, s78, v154
	v_fmac_f32_e32 v148, s79, v154
	v_fmac_f32_e32 v149, s80, v154
	v_fmac_f32_e32 v150, s81, v154
	v_fmac_f32_e32 v151, s82, v154
	v_fmac_f32_e32 v152, s83, v154
	v_fmac_f32_e32 v153, s84, v154
	v_readlane_b32 s88, v128, 44
	v_readlane_b32 s77, v130, 44
	v_readlane_b32 s78, v132, 44
	v_readlane_b32 s79, v134, 44
	v_readlane_b32 s80, v136, 44
	v_readlane_b32 s81, v138, 44
	v_readlane_b32 s82, v140, 44
	v_readlane_b32 s83, v142, 44
	v_readlane_b32 s84, v144, 44
	v_mul_f32_e32 v154, s88, v44
	v_fmac_f32_e32 v146, s77, v154
	v_fmac_f32_e32 v147, s78, v154
	v_fmac_f32_e32 v148, s79, v154
	v_fmac_f32_e32 v149, s80, v154
	v_fmac_f32_e32 v150, s81, v154
	v_fmac_f32_e32 v151, s82, v154
	v_fmac_f32_e32 v152, s83, v154
	v_fmac_f32_e32 v153, s84, v154
	v_readlane_b32 s88, v128, 45
	v_readlane_b32 s77, v130, 45
	v_readlane_b32 s78, v132, 45
	v_readlane_b32 s79, v134, 45
	v_readlane_b32 s80, v136, 45
	v_readlane_b32 s81, v138, 45
	v_readlane_b32 s82, v140, 45
	v_readlane_b32 s83, v142, 45
	v_readlane_b32 s84, v144, 45
	v_mul_f32_e32 v154, s88, v45
	v_fmac_f32_e32 v146, s77, v154
	v_fmac_f32_e32 v147, s78, v154
	v_fmac_f32_e32 v148, s79, v154
	v_fmac_f32_e32 v149, s80, v154
	v_fmac_f32_e32 v150, s81, v154
	v_fmac_f32_e32 v151, s82, v154
	v_fmac_f32_e32 v152, s83, v154
	v_fmac_f32_e32 v153, s84, v154
	v_readlane_b32 s88, v128, 46
	v_readlane_b32 s77, v130, 46
	v_readlane_b32 s78, v132, 46
	v_readlane_b32 s79, v134, 46
	v_readlane_b32 s80, v136, 46
	v_readlane_b32 s81, v138, 46
	v_readlane_b32 s82, v140, 46
	v_readlane_b32 s83, v142, 46
	v_readlane_b32 s84, v144, 46
	v_mul_f32_e32 v154, s88, v46
	v_fmac_f32_e32 v146, s77, v154
	v_fmac_f32_e32 v147, s78, v154
	v_fmac_f32_e32 v148, s79, v154
	v_fmac_f32_e32 v149, s80, v154
	v_fmac_f32_e32 v150, s81, v154
	v_fmac_f32_e32 v151, s82, v154
	v_fmac_f32_e32 v152, s83, v154
	v_fmac_f32_e32 v153, s84, v154
	v_readlane_b32 s88, v128, 47
	v_readlane_b32 s77, v130, 47
	v_readlane_b32 s78, v132, 47
	v_readlane_b32 s79, v134, 47
; __global__ void __launch_bounds__(NTHR, 2) hybrid_fwd(Args args) {
;     ...
;             for (int d = 0; d < 128; ++d) { const float wv = w_pool_out[(size_t)(gb + d) * 1024 + n] * pool_scale[gb + d];
; #pragma unroll
;                 for (int kk = 0; kk < 8; ++kk) a[kk] += pool_w[(size_t)(k0 + kk) * 128 + d] * wv; }
	v_readlane_b32 s80, v136, 47
	v_readlane_b32 s81, v138, 47
	v_readlane_b32 s82, v140, 47
	v_readlane_b32 s83, v142, 47
	v_readlane_b32 s84, v144, 47
	v_mul_f32_e32 v154, s88, v47
	v_fmac_f32_e32 v146, s77, v154
	v_fmac_f32_e32 v147, s78, v154
	v_fmac_f32_e32 v148, s79, v154
	v_fmac_f32_e32 v149, s80, v154
	v_fmac_f32_e32 v150, s81, v154
	v_fmac_f32_e32 v151, s82, v154
	v_fmac_f32_e32 v152, s83, v154
	v_fmac_f32_e32 v153, s84, v154
	v_readlane_b32 s88, v128, 48
	v_readlane_b32 s77, v130, 48
	v_readlane_b32 s78, v132, 48
	v_readlane_b32 s79, v134, 48
	v_readlane_b32 s80, v136, 48
	v_readlane_b32 s81, v138, 48
	v_readlane_b32 s82, v140, 48
	v_readlane_b32 s83, v142, 48
	v_readlane_b32 s84, v144, 48
	v_mul_f32_e32 v154, s88, v48
	v_fmac_f32_e32 v146, s77, v154
	v_fmac_f32_e32 v147, s78, v154
	v_fmac_f32_e32 v148, s79, v154
	v_fmac_f32_e32 v149, s80, v154
	v_fmac_f32_e32 v150, s81, v154
	v_fmac_f32_e32 v151, s82, v154
	v_fmac_f32_e32 v152, s83, v154
	v_fmac_f32_e32 v153, s84, v154
	v_readlane_b32 s88, v128, 49
	v_readlane_b32 s77, v130, 49
	v_readlane_b32 s78, v132, 49
	v_readlane_b32 s79, v134, 49
	v_readlane_b32 s80, v136, 49
	v_readlane_b32 s81, v138, 49
	v_readlane_b32 s82, v140, 49
	v_readlane_b32 s83, v142, 49
	v_readlane_b32 s84, v144, 49
	v_mul_f32_e32 v154, s88, v49
	v_fmac_f32_e32 v146, s77, v154
	v_fmac_f32_e32 v147, s78, v154
	v_fmac_f32_e32 v148, s79, v154
	v_fmac_f32_e32 v149, s80, v154
	v_fmac_f32_e32 v150, s81, v154
	v_fmac_f32_e32 v151, s82, v154
	v_fmac_f32_e32 v152, s83, v154
	v_fmac_f32_e32 v153, s84, v154
	v_readlane_b32 s88, v128, 50
	v_readlane_b32 s77, v130, 50
	v_readlane_b32 s78, v132, 50
	v_readlane_b32 s79, v134, 50
	v_readlane_b32 s80, v136, 50
	v_readlane_b32 s81, v138, 50
	v_readlane_b32 s82, v140, 50
	v_readlane_b32 s83, v142, 50
	v_readlane_b32 s84, v144, 50
	v_mul_f32_e32 v154, s88, v50
	v_fmac_f32_e32 v146, s77, v154
	v_fmac_f32_e32 v147, s78, v154
	v_fmac_f32_e32 v148, s79, v154
	v_fmac_f32_e32 v149, s80, v154
	v_fmac_f32_e32 v150, s81, v154
	v_fmac_f32_e32 v151, s82, v154
	v_fmac_f32_e32 v152, s83, v154
	v_fmac_f32_e32 v153, s84, v154
	v_readlane_b32 s88, v128, 51
	v_readlane_b32 s77, v130, 51
	v_readlane_b32 s78, v132, 51
	v_readlane_b32 s79, v134, 51
	v_readlane_b32 s80, v136, 51
	v_readlane_b32 s81, v138, 51
	v_readlane_b32 s82, v140, 51
	v_readlane_b32 s83, v142, 51
	v_readlane_b32 s84, v144, 51
	v_mul_f32_e32 v154, s88, v51
	v_fmac_f32_e32 v146, s77, v154
	v_fmac_f32_e32 v147, s78, v154
	v_fmac_f32_e32 v148, s79, v154
	v_fmac_f32_e32 v149, s80, v154
	v_fmac_f32_e32 v150, s81, v154
	v_fmac_f32_e32 v151, s82, v154
	v_fmac_f32_e32 v152, s83, v154
	v_fmac_f32_e32 v153, s84, v154
	v_readlane_b32 s88, v128, 52
	v_readlane_b32 s77, v130, 52
	v_readlane_b32 s78, v132, 52
	v_readlane_b32 s79, v134, 52
	v_readlane_b32 s80, v136, 52
	v_readlane_b32 s81, v138, 52
	v_readlane_b32 s82, v140, 52
	v_readlane_b32 s83, v142, 52
	v_readlane_b32 s84, v144, 52
	v_mul_f32_e32 v154, s88, v52
	v_fmac_f32_e32 v146, s77, v154
	v_fmac_f32_e32 v147, s78, v154
	v_fmac_f32_e32 v148, s79, v154
	v_fmac_f32_e32 v149, s80, v154
	v_fmac_f32_e32 v150, s81, v154
	v_fmac_f32_e32 v151, s82, v154
	v_fmac_f32_e32 v152, s83, v154
	v_fmac_f32_e32 v153, s84, v154
	v_readlane_b32 s88, v128, 53
	v_readlane_b32 s77, v130, 53
	v_readlane_b32 s78, v132, 53
	v_readlane_b32 s79, v134, 53
	v_readlane_b32 s80, v136, 53
	v_readlane_b32 s81, v138, 53
	v_readlane_b32 s82, v140, 53
	v_readlane_b32 s83, v142, 53
	v_readlane_b32 s84, v144, 53
	v_mul_f32_e32 v154, s88, v53
	v_fmac_f32_e32 v146, s77, v154
	v_fmac_f32_e32 v147, s78, v154
	v_fmac_f32_e32 v148, s79, v154
	v_fmac_f32_e32 v149, s80, v154
	v_fmac_f32_e32 v150, s81, v154
	v_fmac_f32_e32 v151, s82, v154
	v_fmac_f32_e32 v152, s83, v154
	v_fmac_f32_e32 v153, s84, v154
	v_readlane_b32 s88, v128, 54
	v_readlane_b32 s77, v130, 54
	v_readlane_b32 s78, v132, 54
	v_readlane_b32 s79, v134, 54
	v_readlane_b32 s80, v136, 54
	v_readlane_b32 s81, v138, 54
	v_readlane_b32 s82, v140, 54
	v_readlane_b32 s83, v142, 54
	v_readlane_b32 s84, v144, 54
	v_mul_f32_e32 v154, s88, v54
	v_fmac_f32_e32 v146, s77, v154
	v_fmac_f32_e32 v147, s78, v154
	v_fmac_f32_e32 v148, s79, v154
	v_fmac_f32_e32 v149, s80, v154
	v_fmac_f32_e32 v150, s81, v154
	v_fmac_f32_e32 v151, s82, v154
	v_fmac_f32_e32 v152, s83, v154
	v_fmac_f32_e32 v153, s84, v154
	v_readlane_b32 s88, v128, 55
	v_readlane_b32 s77, v130, 55
	v_readlane_b32 s78, v132, 55
	v_readlane_b32 s79, v134, 55
	v_readlane_b32 s80, v136, 55
	v_readlane_b32 s81, v138, 55
	v_readlane_b32 s82, v140, 55
	v_readlane_b32 s83, v142, 55
	v_readlane_b32 s84, v144, 55
	v_mul_f32_e32 v154, s88, v55
	v_fmac_f32_e32 v146, s77, v154
	v_fmac_f32_e32 v147, s78, v154
	v_fmac_f32_e32 v148, s79, v154
	v_fmac_f32_e32 v149, s80, v154
	v_fmac_f32_e32 v150, s81, v154
	v_fmac_f32_e32 v151, s82, v154
	v_fmac_f32_e32 v152, s83, v154
	v_fmac_f32_e32 v153, s84, v154
	v_readlane_b32 s88, v128, 56
	v_readlane_b32 s77, v130, 56
	v_readlane_b32 s78, v132, 56
	v_readlane_b32 s79, v134, 56
	v_readlane_b32 s80, v136, 56
	v_readlane_b32 s81, v138, 56
	v_readlane_b32 s82, v140, 56
	v_readlane_b32 s83, v142, 56
	v_readlane_b32 s84, v144, 56
	v_mul_f32_e32 v154, s88, v56
	v_fmac_f32_e32 v146, s77, v154
	v_fmac_f32_e32 v147, s78, v154
	v_fmac_f32_e32 v148, s79, v154
	v_fmac_f32_e32 v149, s80, v154
	v_fmac_f32_e32 v150, s81, v154
	v_fmac_f32_e32 v151, s82, v154
	v_fmac_f32_e32 v152, s83, v154
	v_fmac_f32_e32 v153, s84, v154
	v_readlane_b32 s88, v128, 57
	v_readlane_b32 s77, v130, 57
	v_readlane_b32 s78, v132, 57
	v_readlane_b32 s79, v134, 57
	v_readlane_b32 s80, v136, 57
	v_readlane_b32 s81, v138, 57
	v_readlane_b32 s82, v140, 57
; __global__ void __launch_bounds__(NTHR, 2) hybrid_fwd(Args args) {
;     ...
;             for (int d = 0; d < 128; ++d) { const float wv = w_pool_out[(size_t)(gb + d) * 1024 + n] * pool_scale[gb + d];
; #pragma unroll
;                 for (int kk = 0; kk < 8; ++kk) a[kk] += pool_w[(size_t)(k0 + kk) * 128 + d] * wv; }
	v_readlane_b32 s83, v142, 57
	v_readlane_b32 s84, v144, 57
	v_mul_f32_e32 v154, s88, v57
	v_fmac_f32_e32 v146, s77, v154
	v_fmac_f32_e32 v147, s78, v154
	v_fmac_f32_e32 v148, s79, v154
	v_fmac_f32_e32 v149, s80, v154
	v_fmac_f32_e32 v150, s81, v154
	v_fmac_f32_e32 v151, s82, v154
	v_fmac_f32_e32 v152, s83, v154
	v_fmac_f32_e32 v153, s84, v154
	v_readlane_b32 s88, v128, 58
	v_readlane_b32 s77, v130, 58
	v_readlane_b32 s78, v132, 58
	v_readlane_b32 s79, v134, 58
	v_readlane_b32 s80, v136, 58
	v_readlane_b32 s81, v138, 58
	v_readlane_b32 s82, v140, 58
	v_readlane_b32 s83, v142, 58
	v_readlane_b32 s84, v144, 58
	v_mul_f32_e32 v154, s88, v58
	v_fmac_f32_e32 v146, s77, v154
	v_fmac_f32_e32 v147, s78, v154
	v_fmac_f32_e32 v148, s79, v154
	v_fmac_f32_e32 v149, s80, v154
	v_fmac_f32_e32 v150, s81, v154
	v_fmac_f32_e32 v151, s82, v154
	v_fmac_f32_e32 v152, s83, v154
	v_fmac_f32_e32 v153, s84, v154
	v_readlane_b32 s88, v128, 59
	v_readlane_b32 s77, v130, 59
	v_readlane_b32 s78, v132, 59
	v_readlane_b32 s79, v134, 59
	v_readlane_b32 s80, v136, 59
	v_readlane_b32 s81, v138, 59
	v_readlane_b32 s82, v140, 59
	v_readlane_b32 s83, v142, 59
	v_readlane_b32 s84, v144, 59
	v_mul_f32_e32 v154, s88, v59
	v_fmac_f32_e32 v146, s77, v154
	v_fmac_f32_e32 v147, s78, v154
	v_fmac_f32_e32 v148, s79, v154
	v_fmac_f32_e32 v149, s80, v154
	v_fmac_f32_e32 v150, s81, v154
	v_fmac_f32_e32 v151, s82, v154
	v_fmac_f32_e32 v152, s83, v154
	v_fmac_f32_e32 v153, s84, v154
	v_readlane_b32 s88, v128, 60
	v_readlane_b32 s77, v130, 60
	v_readlane_b32 s78, v132, 60
	v_readlane_b32 s79, v134, 60
	v_readlane_b32 s80, v136, 60
	v_readlane_b32 s81, v138, 60
	v_readlane_b32 s82, v140, 60
	v_readlane_b32 s83, v142, 60
	v_readlane_b32 s84, v144, 60
	v_mul_f32_e32 v154, s88, v60
	v_fmac_f32_e32 v146, s77, v154
	v_fmac_f32_e32 v147, s78, v154
	v_fmac_f32_e32 v148, s79, v154
	v_fmac_f32_e32 v149, s80, v154
	v_fmac_f32_e32 v150, s81, v154
	v_fmac_f32_e32 v151, s82, v154
	v_fmac_f32_e32 v152, s83, v154
	v_fmac_f32_e32 v153, s84, v154
	v_readlane_b32 s88, v128, 61
	v_readlane_b32 s77, v130, 61
	v_readlane_b32 s78, v132, 61
	v_readlane_b32 s79, v134, 61
	v_readlane_b32 s80, v136, 61
	v_readlane_b32 s81, v138, 61
	v_readlane_b32 s82, v140, 61
	v_readlane_b32 s83, v142, 61
	v_readlane_b32 s84, v144, 61
	v_mul_f32_e32 v154, s88, v61
	v_fmac_f32_e32 v146, s77, v154
	v_fmac_f32_e32 v147, s78, v154
	v_fmac_f32_e32 v148, s79, v154
	v_fmac_f32_e32 v149, s80, v154
	v_fmac_f32_e32 v150, s81, v154
	v_fmac_f32_e32 v151, s82, v154
	v_fmac_f32_e32 v152, s83, v154
	v_fmac_f32_e32 v153, s84, v154
	v_readlane_b32 s88, v128, 62
	v_readlane_b32 s77, v130, 62
	v_readlane_b32 s78, v132, 62
	v_readlane_b32 s79, v134, 62
	v_readlane_b32 s80, v136, 62
	v_readlane_b32 s81, v138, 62
	v_readlane_b32 s82, v140, 62
	v_readlane_b32 s83, v142, 62
	v_readlane_b32 s84, v144, 62
	v_mul_f32_e32 v154, s88, v62
	v_fmac_f32_e32 v146, s77, v154
	v_fmac_f32_e32 v147, s78, v154
	v_fmac_f32_e32 v148, s79, v154
	v_fmac_f32_e32 v149, s80, v154
	v_fmac_f32_e32 v150, s81, v154
	v_fmac_f32_e32 v151, s82, v154
	v_fmac_f32_e32 v152, s83, v154
	v_fmac_f32_e32 v153, s84, v154
	v_readlane_b32 s88, v128, 63
	v_readlane_b32 s77, v130, 63
	v_readlane_b32 s78, v132, 63
	v_readlane_b32 s79, v134, 63
	v_readlane_b32 s80, v136, 63
	v_readlane_b32 s81, v138, 63
	v_readlane_b32 s82, v140, 63
	v_readlane_b32 s83, v142, 63
	v_readlane_b32 s84, v144, 63
	v_mul_f32_e32 v154, s88, v63
	v_fmac_f32_e32 v146, s77, v154
	v_fmac_f32_e32 v147, s78, v154
	v_fmac_f32_e32 v148, s79, v154
	v_fmac_f32_e32 v149, s80, v154
	v_fmac_f32_e32 v150, s81, v154
	v_fmac_f32_e32 v151, s82, v154
	v_fmac_f32_e32 v152, s83, v154
	v_fmac_f32_e32 v153, s84, v154
	v_readlane_b32 s88, v129, 0
	v_readlane_b32 s77, v131, 0
	v_readlane_b32 s78, v133, 0
	v_readlane_b32 s79, v135, 0
	v_readlane_b32 s80, v137, 0
	v_readlane_b32 s81, v139, 0
	v_readlane_b32 s82, v141, 0
	v_readlane_b32 s83, v143, 0
	v_readlane_b32 s84, v145, 0
	v_mul_f32_e32 v154, s88, v64
	v_fmac_f32_e32 v146, s77, v154
	v_fmac_f32_e32 v147, s78, v154
	v_fmac_f32_e32 v148, s79, v154
	v_fmac_f32_e32 v149, s80, v154
	v_fmac_f32_e32 v150, s81, v154
	v_fmac_f32_e32 v151, s82, v154
	v_fmac_f32_e32 v152, s83, v154
	v_fmac_f32_e32 v153, s84, v154
	v_readlane_b32 s88, v129, 1
	v_readlane_b32 s77, v131, 1
	v_readlane_b32 s78, v133, 1
	v_readlane_b32 s79, v135, 1
	v_readlane_b32 s80, v137, 1
	v_readlane_b32 s81, v139, 1
	v_readlane_b32 s82, v141, 1
	v_readlane_b32 s83, v143, 1
	v_readlane_b32 s84, v145, 1
	v_mul_f32_e32 v154, s88, v65
	v_fmac_f32_e32 v146, s77, v154
	v_fmac_f32_e32 v147, s78, v154
	v_fmac_f32_e32 v148, s79, v154
	v_fmac_f32_e32 v149, s80, v154
	v_fmac_f32_e32 v150, s81, v154
	v_fmac_f32_e32 v151, s82, v154
	v_fmac_f32_e32 v152, s83, v154
	v_fmac_f32_e32 v153, s84, v154
	v_readlane_b32 s88, v129, 2
	v_readlane_b32 s77, v131, 2
	v_readlane_b32 s78, v133, 2
	v_readlane_b32 s79, v135, 2
	v_readlane_b32 s80, v137, 2
	v_readlane_b32 s81, v139, 2
	v_readlane_b32 s82, v141, 2
	v_readlane_b32 s83, v143, 2
	v_readlane_b32 s84, v145, 2
	v_mul_f32_e32 v154, s88, v66
	v_fmac_f32_e32 v146, s77, v154
	v_fmac_f32_e32 v147, s78, v154
	v_fmac_f32_e32 v148, s79, v154
	v_fmac_f32_e32 v149, s80, v154
	v_fmac_f32_e32 v150, s81, v154
	v_fmac_f32_e32 v151, s82, v154
	v_fmac_f32_e32 v152, s83, v154
	v_fmac_f32_e32 v153, s84, v154
	v_readlane_b32 s88, v129, 3
	v_readlane_b32 s77, v131, 3
	v_readlane_b32 s78, v133, 3
	v_readlane_b32 s79, v135, 3
	v_readlane_b32 s80, v137, 3
	v_readlane_b32 s81, v139, 3
	v_readlane_b32 s82, v141, 3
	v_readlane_b32 s83, v143, 3
	v_readlane_b32 s84, v145, 3
	v_mul_f32_e32 v154, s88, v67
	v_fmac_f32_e32 v146, s77, v154
; __global__ void __launch_bounds__(NTHR, 2) hybrid_fwd(Args args) {
;     ...
;             for (int d = 0; d < 128; ++d) { const float wv = w_pool_out[(size_t)(gb + d) * 1024 + n] * pool_scale[gb + d];
; #pragma unroll
;                 for (int kk = 0; kk < 8; ++kk) a[kk] += pool_w[(size_t)(k0 + kk) * 128 + d] * wv; }
	v_fmac_f32_e32 v147, s78, v154
	v_fmac_f32_e32 v148, s79, v154
	v_fmac_f32_e32 v149, s80, v154
	v_fmac_f32_e32 v150, s81, v154
	v_fmac_f32_e32 v151, s82, v154
	v_fmac_f32_e32 v152, s83, v154
	v_fmac_f32_e32 v153, s84, v154
	v_readlane_b32 s88, v129, 4
	v_readlane_b32 s77, v131, 4
	v_readlane_b32 s78, v133, 4
	v_readlane_b32 s79, v135, 4
	v_readlane_b32 s80, v137, 4
	v_readlane_b32 s81, v139, 4
	v_readlane_b32 s82, v141, 4
	v_readlane_b32 s83, v143, 4
	v_readlane_b32 s84, v145, 4
	v_mul_f32_e32 v154, s88, v68
	v_fmac_f32_e32 v146, s77, v154
	v_fmac_f32_e32 v147, s78, v154
	v_fmac_f32_e32 v148, s79, v154
	v_fmac_f32_e32 v149, s80, v154
	v_fmac_f32_e32 v150, s81, v154
	v_fmac_f32_e32 v151, s82, v154
	v_fmac_f32_e32 v152, s83, v154
	v_fmac_f32_e32 v153, s84, v154
	v_readlane_b32 s88, v129, 5
	v_readlane_b32 s77, v131, 5
	v_readlane_b32 s78, v133, 5
	v_readlane_b32 s79, v135, 5
	v_readlane_b32 s80, v137, 5
	v_readlane_b32 s81, v139, 5
	v_readlane_b32 s82, v141, 5
	v_readlane_b32 s83, v143, 5
	v_readlane_b32 s84, v145, 5
	v_mul_f32_e32 v154, s88, v69
	v_fmac_f32_e32 v146, s77, v154
	v_fmac_f32_e32 v147, s78, v154
	v_fmac_f32_e32 v148, s79, v154
	v_fmac_f32_e32 v149, s80, v154
	v_fmac_f32_e32 v150, s81, v154
	v_fmac_f32_e32 v151, s82, v154
	v_fmac_f32_e32 v152, s83, v154
	v_fmac_f32_e32 v153, s84, v154
	v_readlane_b32 s88, v129, 6
	v_readlane_b32 s77, v131, 6
	v_readlane_b32 s78, v133, 6
	v_readlane_b32 s79, v135, 6
	v_readlane_b32 s80, v137, 6
	v_readlane_b32 s81, v139, 6
	v_readlane_b32 s82, v141, 6
	v_readlane_b32 s83, v143, 6
	v_readlane_b32 s84, v145, 6
	v_mul_f32_e32 v154, s88, v70
	v_fmac_f32_e32 v146, s77, v154
	v_fmac_f32_e32 v147, s78, v154
	v_fmac_f32_e32 v148, s79, v154
	v_fmac_f32_e32 v149, s80, v154
	v_fmac_f32_e32 v150, s81, v154
	v_fmac_f32_e32 v151, s82, v154
	v_fmac_f32_e32 v152, s83, v154
	v_fmac_f32_e32 v153, s84, v154
	v_readlane_b32 s88, v129, 7
	v_readlane_b32 s77, v131, 7
	v_readlane_b32 s78, v133, 7
	v_readlane_b32 s79, v135, 7
	v_readlane_b32 s80, v137, 7
	v_readlane_b32 s81, v139, 7
	v_readlane_b32 s82, v141, 7
	v_readlane_b32 s83, v143, 7
	v_readlane_b32 s84, v145, 7
	v_mul_f32_e32 v154, s88, v71
	v_fmac_f32_e32 v146, s77, v154
	v_fmac_f32_e32 v147, s78, v154
	v_fmac_f32_e32 v148, s79, v154
	v_fmac_f32_e32 v149, s80, v154
	v_fmac_f32_e32 v150, s81, v154
	v_fmac_f32_e32 v151, s82, v154
	v_fmac_f32_e32 v152, s83, v154
	v_fmac_f32_e32 v153, s84, v154
	v_readlane_b32 s88, v129, 8
	v_readlane_b32 s77, v131, 8
	v_readlane_b32 s78, v133, 8
	v_readlane_b32 s79, v135, 8
	v_readlane_b32 s80, v137, 8
	v_readlane_b32 s81, v139, 8
	v_readlane_b32 s82, v141, 8
	v_readlane_b32 s83, v143, 8
	v_readlane_b32 s84, v145, 8
	v_mul_f32_e32 v154, s88, v72
	v_fmac_f32_e32 v146, s77, v154
	v_fmac_f32_e32 v147, s78, v154
	v_fmac_f32_e32 v148, s79, v154
	v_fmac_f32_e32 v149, s80, v154
	v_fmac_f32_e32 v150, s81, v154
	v_fmac_f32_e32 v151, s82, v154
	v_fmac_f32_e32 v152, s83, v154
	v_fmac_f32_e32 v153, s84, v154
	v_readlane_b32 s88, v129, 9
	v_readlane_b32 s77, v131, 9
	v_readlane_b32 s78, v133, 9
	v_readlane_b32 s79, v135, 9
	v_readlane_b32 s80, v137, 9
	v_readlane_b32 s81, v139, 9
	v_readlane_b32 s82, v141, 9
	v_readlane_b32 s83, v143, 9
	v_readlane_b32 s84, v145, 9
	v_mul_f32_e32 v154, s88, v73
	v_fmac_f32_e32 v146, s77, v154
	v_fmac_f32_e32 v147, s78, v154
	v_fmac_f32_e32 v148, s79, v154
	v_fmac_f32_e32 v149, s80, v154
	v_fmac_f32_e32 v150, s81, v154
	v_fmac_f32_e32 v151, s82, v154
	v_fmac_f32_e32 v152, s83, v154
	v_fmac_f32_e32 v153, s84, v154
	v_readlane_b32 s88, v129, 10
	v_readlane_b32 s77, v131, 10
	v_readlane_b32 s78, v133, 10
	v_readlane_b32 s79, v135, 10
	v_readlane_b32 s80, v137, 10
	v_readlane_b32 s81, v139, 10
	v_readlane_b32 s82, v141, 10
	v_readlane_b32 s83, v143, 10
	v_readlane_b32 s84, v145, 10
	v_mul_f32_e32 v154, s88, v74
	v_fmac_f32_e32 v146, s77, v154
	v_fmac_f32_e32 v147, s78, v154
	v_fmac_f32_e32 v148, s79, v154
	v_fmac_f32_e32 v149, s80, v154
	v_fmac_f32_e32 v150, s81, v154
	v_fmac_f32_e32 v151, s82, v154
	v_fmac_f32_e32 v152, s83, v154
	v_fmac_f32_e32 v153, s84, v154
	v_readlane_b32 s88, v129, 11
	v_readlane_b32 s77, v131, 11
	v_readlane_b32 s78, v133, 11
	v_readlane_b32 s79, v135, 11
	v_readlane_b32 s80, v137, 11
	v_readlane_b32 s81, v139, 11
	v_readlane_b32 s82, v141, 11
	v_readlane_b32 s83, v143, 11
	v_readlane_b32 s84, v145, 11
	v_mul_f32_e32 v154, s88, v75
	v_fmac_f32_e32 v146, s77, v154
	v_fmac_f32_e32 v147, s78, v154
	v_fmac_f32_e32 v148, s79, v154
	v_fmac_f32_e32 v149, s80, v154
	v_fmac_f32_e32 v150, s81, v154
	v_fmac_f32_e32 v151, s82, v154
	v_fmac_f32_e32 v152, s83, v154
	v_fmac_f32_e32 v153, s84, v154
	v_readlane_b32 s88, v129, 12
	v_readlane_b32 s77, v131, 12
	v_readlane_b32 s78, v133, 12
	v_readlane_b32 s79, v135, 12
	v_readlane_b32 s80, v137, 12
	v_readlane_b32 s81, v139, 12
	v_readlane_b32 s82, v141, 12
	v_readlane_b32 s83, v143, 12
	v_readlane_b32 s84, v145, 12
	v_mul_f32_e32 v154, s88, v76
	v_fmac_f32_e32 v146, s77, v154
	v_fmac_f32_e32 v147, s78, v154
	v_fmac_f32_e32 v148, s79, v154
	v_fmac_f32_e32 v149, s80, v154
	v_fmac_f32_e32 v150, s81, v154
	v_fmac_f32_e32 v151, s82, v154
	v_fmac_f32_e32 v152, s83, v154
	v_fmac_f32_e32 v153, s84, v154
	v_readlane_b32 s88, v129, 13
	v_readlane_b32 s77, v131, 13
	v_readlane_b32 s78, v133, 13
	v_readlane_b32 s79, v135, 13
	v_readlane_b32 s80, v137, 13
	v_readlane_b32 s81, v139, 13
	v_readlane_b32 s82, v141, 13
	v_readlane_b32 s83, v143, 13
	v_readlane_b32 s84, v145, 13
	v_mul_f32_e32 v154, s88, v77
	v_fmac_f32_e32 v146, s77, v154
	v_fmac_f32_e32 v147, s78, v154
	v_fmac_f32_e32 v148, s79, v154
	v_fmac_f32_e32 v149, s80, v154
	v_fmac_f32_e32 v150, s81, v154
; __global__ void __launch_bounds__(NTHR, 2) hybrid_fwd(Args args) {
;     ...
;             for (int d = 0; d < 128; ++d) { const float wv = w_pool_out[(size_t)(gb + d) * 1024 + n] * pool_scale[gb + d];
; #pragma unroll
;                 for (int kk = 0; kk < 8; ++kk) a[kk] += pool_w[(size_t)(k0 + kk) * 128 + d] * wv; }
	v_fmac_f32_e32 v151, s82, v154
	v_fmac_f32_e32 v152, s83, v154
	v_fmac_f32_e32 v153, s84, v154
	v_readlane_b32 s88, v129, 14
	v_readlane_b32 s77, v131, 14
	v_readlane_b32 s78, v133, 14
	v_readlane_b32 s79, v135, 14
	v_readlane_b32 s80, v137, 14
	v_readlane_b32 s81, v139, 14
	v_readlane_b32 s82, v141, 14
	v_readlane_b32 s83, v143, 14
	v_readlane_b32 s84, v145, 14
	v_mul_f32_e32 v154, s88, v78
	v_fmac_f32_e32 v146, s77, v154
	v_fmac_f32_e32 v147, s78, v154
	v_fmac_f32_e32 v148, s79, v154
	v_fmac_f32_e32 v149, s80, v154
	v_fmac_f32_e32 v150, s81, v154
	v_fmac_f32_e32 v151, s82, v154
	v_fmac_f32_e32 v152, s83, v154
	v_fmac_f32_e32 v153, s84, v154
	v_readlane_b32 s88, v129, 15
	v_readlane_b32 s77, v131, 15
	v_readlane_b32 s78, v133, 15
	v_readlane_b32 s79, v135, 15
	v_readlane_b32 s80, v137, 15
	v_readlane_b32 s81, v139, 15
	v_readlane_b32 s82, v141, 15
	v_readlane_b32 s83, v143, 15
	v_readlane_b32 s84, v145, 15
	v_mul_f32_e32 v154, s88, v79
	v_fmac_f32_e32 v146, s77, v154
	v_fmac_f32_e32 v147, s78, v154
	v_fmac_f32_e32 v148, s79, v154
	v_fmac_f32_e32 v149, s80, v154
	v_fmac_f32_e32 v150, s81, v154
	v_fmac_f32_e32 v151, s82, v154
	v_fmac_f32_e32 v152, s83, v154
	v_fmac_f32_e32 v153, s84, v154
	v_readlane_b32 s88, v129, 16
	v_readlane_b32 s77, v131, 16
	v_readlane_b32 s78, v133, 16
	v_readlane_b32 s79, v135, 16
	v_readlane_b32 s80, v137, 16
	v_readlane_b32 s81, v139, 16
	v_readlane_b32 s82, v141, 16
	v_readlane_b32 s83, v143, 16
	v_readlane_b32 s84, v145, 16
	v_mul_f32_e32 v154, s88, v80
	v_fmac_f32_e32 v146, s77, v154
	v_fmac_f32_e32 v147, s78, v154
	v_fmac_f32_e32 v148, s79, v154
	v_fmac_f32_e32 v149, s80, v154
	v_fmac_f32_e32 v150, s81, v154
	v_fmac_f32_e32 v151, s82, v154
	v_fmac_f32_e32 v152, s83, v154
	v_fmac_f32_e32 v153, s84, v154
	v_readlane_b32 s88, v129, 17
	v_readlane_b32 s77, v131, 17
	v_readlane_b32 s78, v133, 17
	v_readlane_b32 s79, v135, 17
	v_readlane_b32 s80, v137, 17
	v_readlane_b32 s81, v139, 17
	v_readlane_b32 s82, v141, 17
	v_readlane_b32 s83, v143, 17
	v_readlane_b32 s84, v145, 17
	v_mul_f32_e32 v154, s88, v81
	v_fmac_f32_e32 v146, s77, v154
	v_fmac_f32_e32 v147, s78, v154
	v_fmac_f32_e32 v148, s79, v154
	v_fmac_f32_e32 v149, s80, v154
	v_fmac_f32_e32 v150, s81, v154
	v_fmac_f32_e32 v151, s82, v154
	v_fmac_f32_e32 v152, s83, v154
	v_fmac_f32_e32 v153, s84, v154
	v_readlane_b32 s88, v129, 18
	v_readlane_b32 s77, v131, 18
	v_readlane_b32 s78, v133, 18
	v_readlane_b32 s79, v135, 18
	v_readlane_b32 s80, v137, 18
	v_readlane_b32 s81, v139, 18
	v_readlane_b32 s82, v141, 18
	v_readlane_b32 s83, v143, 18
	v_readlane_b32 s84, v145, 18
	v_mul_f32_e32 v154, s88, v82
	v_fmac_f32_e32 v146, s77, v154
	v_fmac_f32_e32 v147, s78, v154
	v_fmac_f32_e32 v148, s79, v154
	v_fmac_f32_e32 v149, s80, v154
	v_fmac_f32_e32 v150, s81, v154
	v_fmac_f32_e32 v151, s82, v154
	v_fmac_f32_e32 v152, s83, v154
	v_fmac_f32_e32 v153, s84, v154
	v_readlane_b32 s88, v129, 19
	v_readlane_b32 s77, v131, 19
	v_readlane_b32 s78, v133, 19
	v_readlane_b32 s79, v135, 19
	v_readlane_b32 s80, v137, 19
	v_readlane_b32 s81, v139, 19
	v_readlane_b32 s82, v141, 19
	v_readlane_b32 s83, v143, 19
	v_readlane_b32 s84, v145, 19
	v_mul_f32_e32 v154, s88, v83
	v_fmac_f32_e32 v146, s77, v154
	v_fmac_f32_e32 v147, s78, v154
	v_fmac_f32_e32 v148, s79, v154
	v_fmac_f32_e32 v149, s80, v154
	v_fmac_f32_e32 v150, s81, v154
	v_fmac_f32_e32 v151, s82, v154
	v_fmac_f32_e32 v152, s83, v154
	v_fmac_f32_e32 v153, s84, v154
	v_readlane_b32 s88, v129, 20
	v_readlane_b32 s77, v131, 20
	v_readlane_b32 s78, v133, 20
	v_readlane_b32 s79, v135, 20
	v_readlane_b32 s80, v137, 20
	v_readlane_b32 s81, v139, 20
	v_readlane_b32 s82, v141, 20
	v_readlane_b32 s83, v143, 20
	v_readlane_b32 s84, v145, 20
	v_mul_f32_e32 v154, s88, v84
	v_fmac_f32_e32 v146, s77, v154
	v_fmac_f32_e32 v147, s78, v154
	v_fmac_f32_e32 v148, s79, v154
	v_fmac_f32_e32 v149, s80, v154
	v_fmac_f32_e32 v150, s81, v154
	v_fmac_f32_e32 v151, s82, v154
	v_fmac_f32_e32 v152, s83, v154
	v_fmac_f32_e32 v153, s84, v154
	v_readlane_b32 s88, v129, 21
	v_readlane_b32 s77, v131, 21
	v_readlane_b32 s78, v133, 21
	v_readlane_b32 s79, v135, 21
	v_readlane_b32 s80, v137, 21
	v_readlane_b32 s81, v139, 21
	v_readlane_b32 s82, v141, 21
	v_readlane_b32 s83, v143, 21
	v_readlane_b32 s84, v145, 21
	v_mul_f32_e32 v154, s88, v85
	v_fmac_f32_e32 v146, s77, v154
	v_fmac_f32_e32 v147, s78, v154
	v_fmac_f32_e32 v148, s79, v154
	v_fmac_f32_e32 v149, s80, v154
	v_fmac_f32_e32 v150, s81, v154
	v_fmac_f32_e32 v151, s82, v154
	v_fmac_f32_e32 v152, s83, v154
	v_fmac_f32_e32 v153, s84, v154
	v_readlane_b32 s88, v129, 22
	v_readlane_b32 s77, v131, 22
	v_readlane_b32 s78, v133, 22
	v_readlane_b32 s79, v135, 22
	v_readlane_b32 s80, v137, 22
	v_readlane_b32 s81, v139, 22
	v_readlane_b32 s82, v141, 22
	v_readlane_b32 s83, v143, 22
	v_readlane_b32 s84, v145, 22
	v_mul_f32_e32 v154, s88, v86
	v_fmac_f32_e32 v146, s77, v154
	v_fmac_f32_e32 v147, s78, v154
	v_fmac_f32_e32 v148, s79, v154
	v_fmac_f32_e32 v149, s80, v154
	v_fmac_f32_e32 v150, s81, v154
	v_fmac_f32_e32 v151, s82, v154
	v_fmac_f32_e32 v152, s83, v154
	v_fmac_f32_e32 v153, s84, v154
	v_readlane_b32 s88, v129, 23
	v_readlane_b32 s77, v131, 23
	v_readlane_b32 s78, v133, 23
	v_readlane_b32 s79, v135, 23
	v_readlane_b32 s80, v137, 23
	v_readlane_b32 s81, v139, 23
	v_readlane_b32 s82, v141, 23
	v_readlane_b32 s83, v143, 23
	v_readlane_b32 s84, v145, 23
	v_mul_f32_e32 v154, s88, v87
	v_fmac_f32_e32 v146, s77, v154
	v_fmac_f32_e32 v147, s78, v154
	v_fmac_f32_e32 v148, s79, v154
	v_fmac_f32_e32 v149, s80, v154
	v_fmac_f32_e32 v150, s81, v154
	v_fmac_f32_e32 v151, s82, v154
	v_fmac_f32_e32 v152, s83, v154
; __global__ void __launch_bounds__(NTHR, 2) hybrid_fwd(Args args) {
;     ...
;             for (int d = 0; d < 128; ++d) { const float wv = w_pool_out[(size_t)(gb + d) * 1024 + n] * pool_scale[gb + d];
; #pragma unroll
;                 for (int kk = 0; kk < 8; ++kk) a[kk] += pool_w[(size_t)(k0 + kk) * 128 + d] * wv; }
	v_fmac_f32_e32 v153, s84, v154
	v_readlane_b32 s88, v129, 24
	v_readlane_b32 s77, v131, 24
	v_readlane_b32 s78, v133, 24
	v_readlane_b32 s79, v135, 24
	v_readlane_b32 s80, v137, 24
	v_readlane_b32 s81, v139, 24
	v_readlane_b32 s82, v141, 24
	v_readlane_b32 s83, v143, 24
	v_readlane_b32 s84, v145, 24
	v_mul_f32_e32 v154, s88, v88
	v_fmac_f32_e32 v146, s77, v154
	v_fmac_f32_e32 v147, s78, v154
	v_fmac_f32_e32 v148, s79, v154
	v_fmac_f32_e32 v149, s80, v154
	v_fmac_f32_e32 v150, s81, v154
	v_fmac_f32_e32 v151, s82, v154
	v_fmac_f32_e32 v152, s83, v154
	v_fmac_f32_e32 v153, s84, v154
	v_readlane_b32 s88, v129, 25
	v_readlane_b32 s77, v131, 25
	v_readlane_b32 s78, v133, 25
	v_readlane_b32 s79, v135, 25
	v_readlane_b32 s80, v137, 25
	v_readlane_b32 s81, v139, 25
	v_readlane_b32 s82, v141, 25
	v_readlane_b32 s83, v143, 25
	v_readlane_b32 s84, v145, 25
	v_mul_f32_e32 v154, s88, v89
	v_fmac_f32_e32 v146, s77, v154
	v_fmac_f32_e32 v147, s78, v154
	v_fmac_f32_e32 v148, s79, v154
	v_fmac_f32_e32 v149, s80, v154
	v_fmac_f32_e32 v150, s81, v154
	v_fmac_f32_e32 v151, s82, v154
	v_fmac_f32_e32 v152, s83, v154
	v_fmac_f32_e32 v153, s84, v154
	v_readlane_b32 s88, v129, 26
	v_readlane_b32 s77, v131, 26
	v_readlane_b32 s78, v133, 26
	v_readlane_b32 s79, v135, 26
	v_readlane_b32 s80, v137, 26
	v_readlane_b32 s81, v139, 26
	v_readlane_b32 s82, v141, 26
	v_readlane_b32 s83, v143, 26
	v_readlane_b32 s84, v145, 26
	v_mul_f32_e32 v154, s88, v90
	v_fmac_f32_e32 v146, s77, v154
	v_fmac_f32_e32 v147, s78, v154
	v_fmac_f32_e32 v148, s79, v154
	v_fmac_f32_e32 v149, s80, v154
	v_fmac_f32_e32 v150, s81, v154
	v_fmac_f32_e32 v151, s82, v154
	v_fmac_f32_e32 v152, s83, v154
	v_fmac_f32_e32 v153, s84, v154
	v_readlane_b32 s88, v129, 27
	v_readlane_b32 s77, v131, 27
	v_readlane_b32 s78, v133, 27
	v_readlane_b32 s79, v135, 27
	v_readlane_b32 s80, v137, 27
	v_readlane_b32 s81, v139, 27
	v_readlane_b32 s82, v141, 27
	v_readlane_b32 s83, v143, 27
	v_readlane_b32 s84, v145, 27
	v_mul_f32_e32 v154, s88, v91
	v_fmac_f32_e32 v146, s77, v154
	v_fmac_f32_e32 v147, s78, v154
	v_fmac_f32_e32 v148, s79, v154
	v_fmac_f32_e32 v149, s80, v154
	v_fmac_f32_e32 v150, s81, v154
	v_fmac_f32_e32 v151, s82, v154
	v_fmac_f32_e32 v152, s83, v154
	v_fmac_f32_e32 v153, s84, v154
	v_readlane_b32 s88, v129, 28
	v_readlane_b32 s77, v131, 28
	v_readlane_b32 s78, v133, 28
	v_readlane_b32 s79, v135, 28
	v_readlane_b32 s80, v137, 28
	v_readlane_b32 s81, v139, 28
	v_readlane_b32 s82, v141, 28
	v_readlane_b32 s83, v143, 28
	v_readlane_b32 s84, v145, 28
	v_mul_f32_e32 v154, s88, v92
	v_fmac_f32_e32 v146, s77, v154
	v_fmac_f32_e32 v147, s78, v154
	v_fmac_f32_e32 v148, s79, v154
	v_fmac_f32_e32 v149, s80, v154
	v_fmac_f32_e32 v150, s81, v154
	v_fmac_f32_e32 v151, s82, v154
	v_fmac_f32_e32 v152, s83, v154
	v_fmac_f32_e32 v153, s84, v154
	v_readlane_b32 s88, v129, 29
	v_readlane_b32 s77, v131, 29
	v_readlane_b32 s78, v133, 29
	v_readlane_b32 s79, v135, 29
	v_readlane_b32 s80, v137, 29
	v_readlane_b32 s81, v139, 29
	v_readlane_b32 s82, v141, 29
	v_readlane_b32 s83, v143, 29
	v_readlane_b32 s84, v145, 29
	v_mul_f32_e32 v154, s88, v93
	v_fmac_f32_e32 v146, s77, v154
	v_fmac_f32_e32 v147, s78, v154
	v_fmac_f32_e32 v148, s79, v154
	v_fmac_f32_e32 v149, s80, v154
	v_fmac_f32_e32 v150, s81, v154
	v_fmac_f32_e32 v151, s82, v154
	v_fmac_f32_e32 v152, s83, v154
	v_fmac_f32_e32 v153, s84, v154
	v_readlane_b32 s88, v129, 30
	v_readlane_b32 s77, v131, 30
	v_readlane_b32 s78, v133, 30
	v_readlane_b32 s79, v135, 30
	v_readlane_b32 s80, v137, 30
	v_readlane_b32 s81, v139, 30
	v_readlane_b32 s82, v141, 30
	v_readlane_b32 s83, v143, 30
	v_readlane_b32 s84, v145, 30
	v_mul_f32_e32 v154, s88, v94
	v_fmac_f32_e32 v146, s77, v154
	v_fmac_f32_e32 v147, s78, v154
	v_fmac_f32_e32 v148, s79, v154
	v_fmac_f32_e32 v149, s80, v154
	v_fmac_f32_e32 v150, s81, v154
	v_fmac_f32_e32 v151, s82, v154
	v_fmac_f32_e32 v152, s83, v154
	v_fmac_f32_e32 v153, s84, v154
	v_readlane_b32 s88, v129, 31
	v_readlane_b32 s77, v131, 31
	v_readlane_b32 s78, v133, 31
	v_readlane_b32 s79, v135, 31
	v_readlane_b32 s80, v137, 31
	v_readlane_b32 s81, v139, 31
	v_readlane_b32 s82, v141, 31
	v_readlane_b32 s83, v143, 31
	v_readlane_b32 s84, v145, 31
	v_mul_f32_e32 v154, s88, v95
	v_fmac_f32_e32 v146, s77, v154
	v_fmac_f32_e32 v147, s78, v154
	v_fmac_f32_e32 v148, s79, v154
	v_fmac_f32_e32 v149, s80, v154
	v_fmac_f32_e32 v150, s81, v154
	v_fmac_f32_e32 v151, s82, v154
	v_fmac_f32_e32 v152, s83, v154
	v_fmac_f32_e32 v153, s84, v154
	v_readlane_b32 s88, v129, 32
	v_readlane_b32 s77, v131, 32
	v_readlane_b32 s78, v133, 32
	v_readlane_b32 s79, v135, 32
	v_readlane_b32 s80, v137, 32
	v_readlane_b32 s81, v139, 32
	v_readlane_b32 s82, v141, 32
	v_readlane_b32 s83, v143, 32
	v_readlane_b32 s84, v145, 32
	v_mul_f32_e32 v154, s88, v96
	v_fmac_f32_e32 v146, s77, v154
	v_fmac_f32_e32 v147, s78, v154
	v_fmac_f32_e32 v148, s79, v154
	v_fmac_f32_e32 v149, s80, v154
	v_fmac_f32_e32 v150, s81, v154
	v_fmac_f32_e32 v151, s82, v154
	v_fmac_f32_e32 v152, s83, v154
	v_fmac_f32_e32 v153, s84, v154
	v_readlane_b32 s88, v129, 33
	v_readlane_b32 s77, v131, 33
	v_readlane_b32 s78, v133, 33
	v_readlane_b32 s79, v135, 33
	v_readlane_b32 s80, v137, 33
	v_readlane_b32 s81, v139, 33
	v_readlane_b32 s82, v141, 33
	v_readlane_b32 s83, v143, 33
	v_readlane_b32 s84, v145, 33
	v_mul_f32_e32 v154, s88, v97
	v_fmac_f32_e32 v146, s77, v154
	v_fmac_f32_e32 v147, s78, v154
	v_fmac_f32_e32 v148, s79, v154
	v_fmac_f32_e32 v149, s80, v154
	v_fmac_f32_e32 v150, s81, v154
	v_fmac_f32_e32 v151, s82, v154
	v_fmac_f32_e32 v152, s83, v154
	v_fmac_f32_e32 v153, s84, v154
	v_readlane_b32 s88, v129, 34
	v_readlane_b32 s77, v131, 34
; __global__ void __launch_bounds__(NTHR, 2) hybrid_fwd(Args args) {
;     ...
;             for (int d = 0; d < 128; ++d) { const float wv = w_pool_out[(size_t)(gb + d) * 1024 + n] * pool_scale[gb + d];
; #pragma unroll
;                 for (int kk = 0; kk < 8; ++kk) a[kk] += pool_w[(size_t)(k0 + kk) * 128 + d] * wv; }
	v_readlane_b32 s78, v133, 34
	v_readlane_b32 s79, v135, 34
	v_readlane_b32 s80, v137, 34
	v_readlane_b32 s81, v139, 34
	v_readlane_b32 s82, v141, 34
	v_readlane_b32 s83, v143, 34
	v_readlane_b32 s84, v145, 34
	v_mul_f32_e32 v154, s88, v98
	v_fmac_f32_e32 v146, s77, v154
	v_fmac_f32_e32 v147, s78, v154
	v_fmac_f32_e32 v148, s79, v154
	v_fmac_f32_e32 v149, s80, v154
	v_fmac_f32_e32 v150, s81, v154
	v_fmac_f32_e32 v151, s82, v154
	v_fmac_f32_e32 v152, s83, v154
	v_fmac_f32_e32 v153, s84, v154
	v_readlane_b32 s88, v129, 35
	v_readlane_b32 s77, v131, 35
	v_readlane_b32 s78, v133, 35
	v_readlane_b32 s79, v135, 35
	v_readlane_b32 s80, v137, 35
	v_readlane_b32 s81, v139, 35
	v_readlane_b32 s82, v141, 35
	v_readlane_b32 s83, v143, 35
	v_readlane_b32 s84, v145, 35
	v_mul_f32_e32 v154, s88, v99
	v_fmac_f32_e32 v146, s77, v154
	v_fmac_f32_e32 v147, s78, v154
	v_fmac_f32_e32 v148, s79, v154
	v_fmac_f32_e32 v149, s80, v154
	v_fmac_f32_e32 v150, s81, v154
	v_fmac_f32_e32 v151, s82, v154
	v_fmac_f32_e32 v152, s83, v154
	v_fmac_f32_e32 v153, s84, v154
	v_readlane_b32 s88, v129, 36
	v_readlane_b32 s77, v131, 36
	v_readlane_b32 s78, v133, 36
	v_readlane_b32 s79, v135, 36
	v_readlane_b32 s80, v137, 36
	v_readlane_b32 s81, v139, 36
	v_readlane_b32 s82, v141, 36
	v_readlane_b32 s83, v143, 36
	v_readlane_b32 s84, v145, 36
	v_mul_f32_e32 v154, s88, v100
	v_fmac_f32_e32 v146, s77, v154
	v_fmac_f32_e32 v147, s78, v154
	v_fmac_f32_e32 v148, s79, v154
	v_fmac_f32_e32 v149, s80, v154
	v_fmac_f32_e32 v150, s81, v154
	v_fmac_f32_e32 v151, s82, v154
	v_fmac_f32_e32 v152, s83, v154
	v_fmac_f32_e32 v153, s84, v154
	v_readlane_b32 s88, v129, 37
	v_readlane_b32 s77, v131, 37
	v_readlane_b32 s78, v133, 37
	v_readlane_b32 s79, v135, 37
	v_readlane_b32 s80, v137, 37
	v_readlane_b32 s81, v139, 37
	v_readlane_b32 s82, v141, 37
	v_readlane_b32 s83, v143, 37
	v_readlane_b32 s84, v145, 37
	v_mul_f32_e32 v154, s88, v101
	v_fmac_f32_e32 v146, s77, v154
	v_fmac_f32_e32 v147, s78, v154
	v_fmac_f32_e32 v148, s79, v154
	v_fmac_f32_e32 v149, s80, v154
	v_fmac_f32_e32 v150, s81, v154
	v_fmac_f32_e32 v151, s82, v154
	v_fmac_f32_e32 v152, s83, v154
	v_fmac_f32_e32 v153, s84, v154
	v_readlane_b32 s88, v129, 38
	v_readlane_b32 s77, v131, 38
	v_readlane_b32 s78, v133, 38
	v_readlane_b32 s79, v135, 38
	v_readlane_b32 s80, v137, 38
	v_readlane_b32 s81, v139, 38
	v_readlane_b32 s82, v141, 38
	v_readlane_b32 s83, v143, 38
	v_readlane_b32 s84, v145, 38
	v_mul_f32_e32 v154, s88, v102
	v_fmac_f32_e32 v146, s77, v154
	v_fmac_f32_e32 v147, s78, v154
	v_fmac_f32_e32 v148, s79, v154
	v_fmac_f32_e32 v149, s80, v154
	v_fmac_f32_e32 v150, s81, v154
	v_fmac_f32_e32 v151, s82, v154
	v_fmac_f32_e32 v152, s83, v154
	v_fmac_f32_e32 v153, s84, v154
	v_readlane_b32 s88, v129, 39
	v_readlane_b32 s77, v131, 39
	v_readlane_b32 s78, v133, 39
	v_readlane_b32 s79, v135, 39
	v_readlane_b32 s80, v137, 39
	v_readlane_b32 s81, v139, 39
	v_readlane_b32 s82, v141, 39
	v_readlane_b32 s83, v143, 39
	v_readlane_b32 s84, v145, 39
	v_mul_f32_e32 v154, s88, v103
	v_fmac_f32_e32 v146, s77, v154
	v_fmac_f32_e32 v147, s78, v154
	v_fmac_f32_e32 v148, s79, v154
	v_fmac_f32_e32 v149, s80, v154
	v_fmac_f32_e32 v150, s81, v154
	v_fmac_f32_e32 v151, s82, v154
	v_fmac_f32_e32 v152, s83, v154
	v_fmac_f32_e32 v153, s84, v154
	v_readlane_b32 s88, v129, 40
	v_readlane_b32 s77, v131, 40
	v_readlane_b32 s78, v133, 40
	v_readlane_b32 s79, v135, 40
	v_readlane_b32 s80, v137, 40
	v_readlane_b32 s81, v139, 40
	v_readlane_b32 s82, v141, 40
	v_readlane_b32 s83, v143, 40
	v_readlane_b32 s84, v145, 40
	v_mul_f32_e32 v154, s88, v104
	v_fmac_f32_e32 v146, s77, v154
	v_fmac_f32_e32 v147, s78, v154
	v_fmac_f32_e32 v148, s79, v154
	v_fmac_f32_e32 v149, s80, v154
	v_fmac_f32_e32 v150, s81, v154
	v_fmac_f32_e32 v151, s82, v154
	v_fmac_f32_e32 v152, s83, v154
	v_fmac_f32_e32 v153, s84, v154
	v_readlane_b32 s88, v129, 41
	v_readlane_b32 s77, v131, 41
	v_readlane_b32 s78, v133, 41
	v_readlane_b32 s79, v135, 41
	v_readlane_b32 s80, v137, 41
	v_readlane_b32 s81, v139, 41
	v_readlane_b32 s82, v141, 41
	v_readlane_b32 s83, v143, 41
	v_readlane_b32 s84, v145, 41
	v_mul_f32_e32 v154, s88, v105
	v_fmac_f32_e32 v146, s77, v154
	v_fmac_f32_e32 v147, s78, v154
	v_fmac_f32_e32 v148, s79, v154
	v_fmac_f32_e32 v149, s80, v154
	v_fmac_f32_e32 v150, s81, v154
	v_fmac_f32_e32 v151, s82, v154
	v_fmac_f32_e32 v152, s83, v154
	v_fmac_f32_e32 v153, s84, v154
	v_readlane_b32 s88, v129, 42
	v_readlane_b32 s77, v131, 42
	v_readlane_b32 s78, v133, 42
	v_readlane_b32 s79, v135, 42
	v_readlane_b32 s80, v137, 42
	v_readlane_b32 s81, v139, 42
	v_readlane_b32 s82, v141, 42
	v_readlane_b32 s83, v143, 42
	v_readlane_b32 s84, v145, 42
	v_mul_f32_e32 v154, s88, v106
	v_fmac_f32_e32 v146, s77, v154
	v_fmac_f32_e32 v147, s78, v154
	v_fmac_f32_e32 v148, s79, v154
	v_fmac_f32_e32 v149, s80, v154
	v_fmac_f32_e32 v150, s81, v154
	v_fmac_f32_e32 v151, s82, v154
	v_fmac_f32_e32 v152, s83, v154
	v_fmac_f32_e32 v153, s84, v154
	v_readlane_b32 s88, v129, 43
	v_readlane_b32 s77, v131, 43
	v_readlane_b32 s78, v133, 43
	v_readlane_b32 s79, v135, 43
	v_readlane_b32 s80, v137, 43
	v_readlane_b32 s81, v139, 43
	v_readlane_b32 s82, v141, 43
	v_readlane_b32 s83, v143, 43
	v_readlane_b32 s84, v145, 43
	v_mul_f32_e32 v154, s88, v107
	v_fmac_f32_e32 v146, s77, v154
	v_fmac_f32_e32 v147, s78, v154
	v_fmac_f32_e32 v148, s79, v154
	v_fmac_f32_e32 v149, s80, v154
	v_fmac_f32_e32 v150, s81, v154
	v_fmac_f32_e32 v151, s82, v154
	v_fmac_f32_e32 v152, s83, v154
	v_fmac_f32_e32 v153, s84, v154
	v_readlane_b32 s88, v129, 44
	v_readlane_b32 s77, v131, 44
	v_readlane_b32 s78, v133, 44
	v_readlane_b32 s79, v135, 44
; __global__ void __launch_bounds__(NTHR, 2) hybrid_fwd(Args args) {
;     ...
;             for (int d = 0; d < 128; ++d) { const float wv = w_pool_out[(size_t)(gb + d) * 1024 + n] * pool_scale[gb + d];
; #pragma unroll
;                 for (int kk = 0; kk < 8; ++kk) a[kk] += pool_w[(size_t)(k0 + kk) * 128 + d] * wv; }
	v_readlane_b32 s80, v137, 44
	v_readlane_b32 s81, v139, 44
	v_readlane_b32 s82, v141, 44
	v_readlane_b32 s83, v143, 44
	v_readlane_b32 s84, v145, 44
	v_mul_f32_e32 v154, s88, v108
	v_fmac_f32_e32 v146, s77, v154
	v_fmac_f32_e32 v147, s78, v154
	v_fmac_f32_e32 v148, s79, v154
	v_fmac_f32_e32 v149, s80, v154
	v_fmac_f32_e32 v150, s81, v154
	v_fmac_f32_e32 v151, s82, v154
	v_fmac_f32_e32 v152, s83, v154
	v_fmac_f32_e32 v153, s84, v154
	v_readlane_b32 s88, v129, 45
	v_readlane_b32 s77, v131, 45
	v_readlane_b32 s78, v133, 45
	v_readlane_b32 s79, v135, 45
	v_readlane_b32 s80, v137, 45
	v_readlane_b32 s81, v139, 45
	v_readlane_b32 s82, v141, 45
	v_readlane_b32 s83, v143, 45
	v_readlane_b32 s84, v145, 45
	v_mul_f32_e32 v154, s88, v109
	v_fmac_f32_e32 v146, s77, v154
	v_fmac_f32_e32 v147, s78, v154
	v_fmac_f32_e32 v148, s79, v154
	v_fmac_f32_e32 v149, s80, v154
	v_fmac_f32_e32 v150, s81, v154
	v_fmac_f32_e32 v151, s82, v154
	v_fmac_f32_e32 v152, s83, v154
	v_fmac_f32_e32 v153, s84, v154
	v_readlane_b32 s88, v129, 46
	v_readlane_b32 s77, v131, 46
	v_readlane_b32 s78, v133, 46
	v_readlane_b32 s79, v135, 46
	v_readlane_b32 s80, v137, 46
	v_readlane_b32 s81, v139, 46
	v_readlane_b32 s82, v141, 46
	v_readlane_b32 s83, v143, 46
	v_readlane_b32 s84, v145, 46
	v_mul_f32_e32 v154, s88, v110
	v_fmac_f32_e32 v146, s77, v154
	v_fmac_f32_e32 v147, s78, v154
	v_fmac_f32_e32 v148, s79, v154
	v_fmac_f32_e32 v149, s80, v154
	v_fmac_f32_e32 v150, s81, v154
	v_fmac_f32_e32 v151, s82, v154
	v_fmac_f32_e32 v152, s83, v154
	v_fmac_f32_e32 v153, s84, v154
	v_readlane_b32 s88, v129, 47
	v_readlane_b32 s77, v131, 47
	v_readlane_b32 s78, v133, 47
	v_readlane_b32 s79, v135, 47
	v_readlane_b32 s80, v137, 47
	v_readlane_b32 s81, v139, 47
	v_readlane_b32 s82, v141, 47
	v_readlane_b32 s83, v143, 47
	v_readlane_b32 s84, v145, 47
	v_mul_f32_e32 v154, s88, v111
	v_fmac_f32_e32 v146, s77, v154
	v_fmac_f32_e32 v147, s78, v154
	v_fmac_f32_e32 v148, s79, v154
	v_fmac_f32_e32 v149, s80, v154
	v_fmac_f32_e32 v150, s81, v154
	v_fmac_f32_e32 v151, s82, v154
	v_fmac_f32_e32 v152, s83, v154
	v_fmac_f32_e32 v153, s84, v154
	v_readlane_b32 s88, v129, 48
	v_readlane_b32 s77, v131, 48
	v_readlane_b32 s78, v133, 48
	v_readlane_b32 s79, v135, 48
	v_readlane_b32 s80, v137, 48
	v_readlane_b32 s81, v139, 48
	v_readlane_b32 s82, v141, 48
	v_readlane_b32 s83, v143, 48
	v_readlane_b32 s84, v145, 48
	v_mul_f32_e32 v154, s88, v112
	v_fmac_f32_e32 v146, s77, v154
	v_fmac_f32_e32 v147, s78, v154
	v_fmac_f32_e32 v148, s79, v154
	v_fmac_f32_e32 v149, s80, v154
	v_fmac_f32_e32 v150, s81, v154
	v_fmac_f32_e32 v151, s82, v154
	v_fmac_f32_e32 v152, s83, v154
	v_fmac_f32_e32 v153, s84, v154
	v_readlane_b32 s88, v129, 49
	v_readlane_b32 s77, v131, 49
	v_readlane_b32 s78, v133, 49
	v_readlane_b32 s79, v135, 49
	v_readlane_b32 s80, v137, 49
	v_readlane_b32 s81, v139, 49
	v_readlane_b32 s82, v141, 49
	v_readlane_b32 s83, v143, 49
	v_readlane_b32 s84, v145, 49
	v_mul_f32_e32 v154, s88, v113
	v_fmac_f32_e32 v146, s77, v154
	v_fmac_f32_e32 v147, s78, v154
	v_fmac_f32_e32 v148, s79, v154
	v_fmac_f32_e32 v149, s80, v154
	v_fmac_f32_e32 v150, s81, v154
	v_fmac_f32_e32 v151, s82, v154
	v_fmac_f32_e32 v152, s83, v154
	v_fmac_f32_e32 v153, s84, v154
	v_readlane_b32 s88, v129, 50
	v_readlane_b32 s77, v131, 50
	v_readlane_b32 s78, v133, 50
	v_readlane_b32 s79, v135, 50
	v_readlane_b32 s80, v137, 50
	v_readlane_b32 s81, v139, 50
	v_readlane_b32 s82, v141, 50
	v_readlane_b32 s83, v143, 50
	v_readlane_b32 s84, v145, 50
	v_mul_f32_e32 v154, s88, v114
	v_fmac_f32_e32 v146, s77, v154
	v_fmac_f32_e32 v147, s78, v154
	v_fmac_f32_e32 v148, s79, v154
	v_fmac_f32_e32 v149, s80, v154
	v_fmac_f32_e32 v150, s81, v154
	v_fmac_f32_e32 v151, s82, v154
	v_fmac_f32_e32 v152, s83, v154
	v_fmac_f32_e32 v153, s84, v154
	v_readlane_b32 s88, v129, 51
	v_readlane_b32 s77, v131, 51
	v_readlane_b32 s78, v133, 51
	v_readlane_b32 s79, v135, 51
	v_readlane_b32 s80, v137, 51
	v_readlane_b32 s81, v139, 51
	v_readlane_b32 s82, v141, 51
	v_readlane_b32 s83, v143, 51
	v_readlane_b32 s84, v145, 51
	v_mul_f32_e32 v154, s88, v115
	v_fmac_f32_e32 v146, s77, v154
	v_fmac_f32_e32 v147, s78, v154
	v_fmac_f32_e32 v148, s79, v154
	v_fmac_f32_e32 v149, s80, v154
	v_fmac_f32_e32 v150, s81, v154
	v_fmac_f32_e32 v151, s82, v154
	v_fmac_f32_e32 v152, s83, v154
	v_fmac_f32_e32 v153, s84, v154
	v_readlane_b32 s88, v129, 52
	v_readlane_b32 s77, v131, 52
	v_readlane_b32 s78, v133, 52
	v_readlane_b32 s79, v135, 52
	v_readlane_b32 s80, v137, 52
	v_readlane_b32 s81, v139, 52
	v_readlane_b32 s82, v141, 52
	v_readlane_b32 s83, v143, 52
	v_readlane_b32 s84, v145, 52
	v_mul_f32_e32 v154, s88, v116
	v_fmac_f32_e32 v146, s77, v154
	v_fmac_f32_e32 v147, s78, v154
	v_fmac_f32_e32 v148, s79, v154
	v_fmac_f32_e32 v149, s80, v154
	v_fmac_f32_e32 v150, s81, v154
	v_fmac_f32_e32 v151, s82, v154
	v_fmac_f32_e32 v152, s83, v154
	v_fmac_f32_e32 v153, s84, v154
	v_readlane_b32 s88, v129, 53
	v_readlane_b32 s77, v131, 53
	v_readlane_b32 s78, v133, 53
	v_readlane_b32 s79, v135, 53
	v_readlane_b32 s80, v137, 53
	v_readlane_b32 s81, v139, 53
	v_readlane_b32 s82, v141, 53
	v_readlane_b32 s83, v143, 53
	v_readlane_b32 s84, v145, 53
	v_mul_f32_e32 v154, s88, v117
	v_fmac_f32_e32 v146, s77, v154
	v_fmac_f32_e32 v147, s78, v154
	v_fmac_f32_e32 v148, s79, v154
	v_fmac_f32_e32 v149, s80, v154
	v_fmac_f32_e32 v150, s81, v154
	v_fmac_f32_e32 v151, s82, v154
	v_fmac_f32_e32 v152, s83, v154
	v_fmac_f32_e32 v153, s84, v154
	v_readlane_b32 s88, v129, 54
	v_readlane_b32 s77, v131, 54
	v_readlane_b32 s78, v133, 54
	v_readlane_b32 s79, v135, 54
	v_readlane_b32 s80, v137, 54
	v_readlane_b32 s81, v139, 54
; __device__ __forceinline__ unsigned pk2(float lo, float hi) { return pg8::cvt_pk_bf16(lo, hi); }
; __global__ void __launch_bounds__(NTHR, 2) hybrid_fwd(Args args) {
;     ...
;             for (int d = 0; d < 128; ++d) { const float wv = w_pool_out[(size_t)(gb + d) * 1024 + n] * pool_scale[gb + d];
; #pragma unroll
;                 for (int kk = 0; kk < 8; ++kk) a[kk] += pool_w[(size_t)(k0 + kk) * 128 + d] * wv; }
;             u32x4 o; o.x = pk2(a[0], a[1]); o.y = pk2(a[2], a[3]); o.z = pk2(a[4], a[5]); o.w = pk2(a[6], a[7]);
;             *(u32x4*)(Wmix + (size_t)n * 1024 + k0) = o; }
	v_readlane_b32 s82, v141, 54
	v_readlane_b32 s83, v143, 54
	v_readlane_b32 s84, v145, 54
	v_mul_f32_e32 v154, s88, v118
	v_fmac_f32_e32 v146, s77, v154
	v_fmac_f32_e32 v147, s78, v154
	v_fmac_f32_e32 v148, s79, v154
	v_fmac_f32_e32 v149, s80, v154
	v_fmac_f32_e32 v150, s81, v154
	v_fmac_f32_e32 v151, s82, v154
	v_fmac_f32_e32 v152, s83, v154
	v_fmac_f32_e32 v153, s84, v154
	v_readlane_b32 s88, v129, 55
	v_readlane_b32 s77, v131, 55
	v_readlane_b32 s78, v133, 55
	v_readlane_b32 s79, v135, 55
	v_readlane_b32 s80, v137, 55
	v_readlane_b32 s81, v139, 55
	v_readlane_b32 s82, v141, 55
	v_readlane_b32 s83, v143, 55
	v_readlane_b32 s84, v145, 55
	v_mul_f32_e32 v154, s88, v119
	v_fmac_f32_e32 v146, s77, v154
	v_fmac_f32_e32 v147, s78, v154
	v_fmac_f32_e32 v148, s79, v154
	v_fmac_f32_e32 v149, s80, v154
	v_fmac_f32_e32 v150, s81, v154
	v_fmac_f32_e32 v151, s82, v154
	v_fmac_f32_e32 v152, s83, v154
	v_fmac_f32_e32 v153, s84, v154
	v_readlane_b32 s88, v129, 56
	v_readlane_b32 s77, v131, 56
	v_readlane_b32 s78, v133, 56
	v_readlane_b32 s79, v135, 56
	v_readlane_b32 s80, v137, 56
	v_readlane_b32 s81, v139, 56
	v_readlane_b32 s82, v141, 56
	v_readlane_b32 s83, v143, 56
	v_readlane_b32 s84, v145, 56
	v_mul_f32_e32 v154, s88, v120
	v_fmac_f32_e32 v146, s77, v154
	v_fmac_f32_e32 v147, s78, v154
	v_fmac_f32_e32 v148, s79, v154
	v_fmac_f32_e32 v149, s80, v154
	v_fmac_f32_e32 v150, s81, v154
	v_fmac_f32_e32 v151, s82, v154
	v_fmac_f32_e32 v152, s83, v154
	v_fmac_f32_e32 v153, s84, v154
	v_readlane_b32 s88, v129, 57
	v_readlane_b32 s77, v131, 57
	v_readlane_b32 s78, v133, 57
	v_readlane_b32 s79, v135, 57
	v_readlane_b32 s80, v137, 57
	v_readlane_b32 s81, v139, 57
	v_readlane_b32 s82, v141, 57
	v_readlane_b32 s83, v143, 57
	v_readlane_b32 s84, v145, 57
	v_mul_f32_e32 v154, s88, v121
	v_fmac_f32_e32 v146, s77, v154
	v_fmac_f32_e32 v147, s78, v154
	v_fmac_f32_e32 v148, s79, v154
	v_fmac_f32_e32 v149, s80, v154
	v_fmac_f32_e32 v150, s81, v154
	v_fmac_f32_e32 v151, s82, v154
	v_fmac_f32_e32 v152, s83, v154
	v_fmac_f32_e32 v153, s84, v154
	v_readlane_b32 s88, v129, 58
	v_readlane_b32 s77, v131, 58
	v_readlane_b32 s78, v133, 58
	v_readlane_b32 s79, v135, 58
	v_readlane_b32 s80, v137, 58
	v_readlane_b32 s81, v139, 58
	v_readlane_b32 s82, v141, 58
	v_readlane_b32 s83, v143, 58
	v_readlane_b32 s84, v145, 58
	v_mul_f32_e32 v154, s88, v122
	v_fmac_f32_e32 v146, s77, v154
	v_fmac_f32_e32 v147, s78, v154
	v_fmac_f32_e32 v148, s79, v154
	v_fmac_f32_e32 v149, s80, v154
	v_fmac_f32_e32 v150, s81, v154
	v_fmac_f32_e32 v151, s82, v154
	v_fmac_f32_e32 v152, s83, v154
	v_fmac_f32_e32 v153, s84, v154
	v_readlane_b32 s88, v129, 59
	v_readlane_b32 s77, v131, 59
	v_readlane_b32 s78, v133, 59
	v_readlane_b32 s79, v135, 59
	v_readlane_b32 s80, v137, 59
	v_readlane_b32 s81, v139, 59
	v_readlane_b32 s82, v141, 59
	v_readlane_b32 s83, v143, 59
	v_readlane_b32 s84, v145, 59
	v_mul_f32_e32 v154, s88, v123
	v_fmac_f32_e32 v146, s77, v154
	v_fmac_f32_e32 v147, s78, v154
	v_fmac_f32_e32 v148, s79, v154
	v_fmac_f32_e32 v149, s80, v154
	v_fmac_f32_e32 v150, s81, v154
	v_fmac_f32_e32 v151, s82, v154
	v_fmac_f32_e32 v152, s83, v154
	v_fmac_f32_e32 v153, s84, v154
	v_readlane_b32 s88, v129, 60
	v_readlane_b32 s77, v131, 60
	v_readlane_b32 s78, v133, 60
	v_readlane_b32 s79, v135, 60
	v_readlane_b32 s80, v137, 60
	v_readlane_b32 s81, v139, 60
	v_readlane_b32 s82, v141, 60
	v_readlane_b32 s83, v143, 60
	v_readlane_b32 s84, v145, 60
	v_mul_f32_e32 v154, s88, v124
	v_fmac_f32_e32 v146, s77, v154
	v_fmac_f32_e32 v147, s78, v154
	v_fmac_f32_e32 v148, s79, v154
	v_fmac_f32_e32 v149, s80, v154
	v_fmac_f32_e32 v150, s81, v154
	v_fmac_f32_e32 v151, s82, v154
	v_fmac_f32_e32 v152, s83, v154
	v_fmac_f32_e32 v153, s84, v154
	v_readlane_b32 s88, v129, 61
	v_readlane_b32 s77, v131, 61
	v_readlane_b32 s78, v133, 61
	v_readlane_b32 s79, v135, 61
	v_readlane_b32 s80, v137, 61
	v_readlane_b32 s81, v139, 61
	v_readlane_b32 s82, v141, 61
	v_readlane_b32 s83, v143, 61
	v_readlane_b32 s84, v145, 61
	v_mul_f32_e32 v154, s88, v125
	v_fmac_f32_e32 v146, s77, v154
	v_fmac_f32_e32 v147, s78, v154
	v_fmac_f32_e32 v148, s79, v154
	v_fmac_f32_e32 v149, s80, v154
	v_fmac_f32_e32 v150, s81, v154
	v_fmac_f32_e32 v151, s82, v154
	v_fmac_f32_e32 v152, s83, v154
	v_fmac_f32_e32 v153, s84, v154
	v_readlane_b32 s88, v129, 62
	v_readlane_b32 s77, v131, 62
	v_readlane_b32 s78, v133, 62
	v_readlane_b32 s79, v135, 62
	v_readlane_b32 s80, v137, 62
	v_readlane_b32 s81, v139, 62
	v_readlane_b32 s82, v141, 62
	v_readlane_b32 s83, v143, 62
	v_readlane_b32 s84, v145, 62
	v_mul_f32_e32 v154, s88, v126
	v_fmac_f32_e32 v146, s77, v154
	v_fmac_f32_e32 v147, s78, v154
	v_fmac_f32_e32 v148, s79, v154
	v_fmac_f32_e32 v149, s80, v154
	v_fmac_f32_e32 v150, s81, v154
	v_fmac_f32_e32 v151, s82, v154
	v_fmac_f32_e32 v152, s83, v154
	v_fmac_f32_e32 v153, s84, v154
	v_readlane_b32 s88, v129, 63
	v_readlane_b32 s77, v131, 63
	v_readlane_b32 s78, v133, 63
	v_readlane_b32 s79, v135, 63
	v_readlane_b32 s80, v137, 63
	v_readlane_b32 s81, v139, 63
	v_readlane_b32 s82, v141, 63
	v_readlane_b32 s83, v143, 63
	v_readlane_b32 s84, v145, 63
	v_mul_f32_e32 v154, s88, v127
	v_fmac_f32_e32 v146, s77, v154
	v_fmac_f32_e32 v147, s78, v154
	v_fmac_f32_e32 v148, s79, v154
	v_fmac_f32_e32 v149, s80, v154
	v_fmac_f32_e32 v150, s81, v154
	v_fmac_f32_e32 v151, s82, v154
	v_fmac_f32_e32 v152, s83, v154
	v_fmac_f32_e32 v153, s84, v154
	v_cvt_pk_bf16_f32 v72, v146, v147
	v_cvt_pk_bf16_f32 v73, v148, v149
	v_cvt_pk_bf16_f32 v74, v150, v151
	v_cvt_pk_bf16_f32 v75, v152, v153
	s_lshl_b32 s79, s27, 1
	s_add_u32 s86, s18, 0x900000
	s_addc_u32 s87, s19, 0
	s_add_u32 s86, s86, s79
	s_addc_u32 s87, s87, 0
	v_lshlrev_b32_e32 v158, 11, v155
	global_store_dwordx4 v158, v[72:75], s[86:87] sc1
.Ldef_fold_done:
	s_waitcnt vmcnt(0) lgkmcnt(0)
	s_barrier
	s_cmp_lg_u32 s74, 0
	s_cbranch_scc1 .Ldef_pub_done
	v_cmp_eq_u32_e32 vcc, 0, v212
	s_and_saveexec_b64 s[80:81], vcc
	s_cbranch_execz .Ldef_pub_restore
	v_mov_b32_e32 v0, 0
	v_mov_b32_e32 v1, 1
	global_atomic_add v0, v1, s[18:19] offset:2816
